# v32 with GEMM K-loop priorities swapped (load segment prio 1, MFMA block prio 0)
# speedup vs baseline: 1.0194x; 1.0112x over previous
; #define PG8_STAGE(bufoff, gbase, voff) do { _Pragma("unroll") for (int _i = 0; _i < 2; ++_i) \
;         __builtin_amdgcn_global_load_lds((const unsigned*)((const char*)(gbase) + (voff)[_i]), (PG8_LAS unsigned*)(lds + (bufoff) + ldsw + _i * 8192), 16, 0, 0); } while (0)
; #define PG8_LDA(dst, b, h) do { _Pragma("unroll") for (int m = 0; m < 4; ++m) _Pragma("unroll") for (int k = 0; k < 2; ++k) dst[m][k] = *(const PG8_LAS bf16x8*)(lds + PG8_SA(b, h) + aoff + m * 2048 + k * 1024); } while (0)
; #define PG8_LDB(dst, b, h) do { _Pragma("unroll") for (int n = 0; n < 2; ++n) _Pragma("unroll") for (int k = 0; k < 2; ++k) dst[n][k] = *(const PG8_LAS bf16x8*)(lds + PG8_SB(b, h) + boff + n * 2048 + k * 1024); } while (0)
; #define PG8_MMA(ai, bj, At, Bt) do { __builtin_amdgcn_s_setprio(1); _Pragma("unroll") for (int m = 0; m < 4; ++m) _Pragma("unroll") for (int n = 0; n < 2; ++n) _Pragma("unroll") for (int k = 0; k < 2; ++k) \
;         acc[ai][bj][m][n] = __builtin_amdgcn_mfma_f32_16x16x32_bf16(Bt[n][k], At[m][k], acc[ai][bj][m][n], 0, 0, 0); __builtin_amdgcn_s_setprio(0); } while (0)
; #define PG8_WAIT_V(n) asm volatile("s_waitcnt vmcnt(" #n ")" ::: "memory")
; #define PG8_WAIT_L(n) asm volatile("s_waitcnt lgkmcnt(" #n ")" ::: "memory")
; template <class Epi, class Sched, bool ALIGN_EPI = false, bool SP2 = false>
; __device__ __forceinline__ void gemm_phase(PG8_LAS unsigned char* lds, const Gemm g, const Sched& S, const Epi& E, int wv) {
;     ...
;             const bool last = (t == nt - 2);
;             const char* a1 = cA + (size_t)(t + 1) * kstep;
;             const char* a2 = last ? nA : cA + (size_t)(t + 2) * kstep; const char* b2 = last ? nB : cB + (size_t)(t + 2) * kstep;
;             const char* a3 = a2 + kstep; const char* b3 = b2 + kstep;
;             if (last && has_next) S.a_ready(nxt);
;             if constexpr (SP2) {
;             PG8_LDB(B0, 0, 0); PG8_LDB(B1, 0, 1); PG8_SCHED; PG8_LDA(At, 0, 0); PG8_STAGE(PG8_SA(1, 1), a1 + hstepA, voffA);
;             PG8_WAIT_V(8); PG8_WAIT_L(0); PG8_BAR; PG8_MMA(0, 0, At, B0); PG8_MMA(0, 1, At, B1); PG8_BAR; PG8_SCHED;
;             PG8_LDA(At, 0, 1); PG8_STAGE(PG8_SB(0, 0), b2, voffB); PG8_STAGE(PG8_SB(0, 1), b2 + hstepB, voffB); PG8_STAGE(PG8_SA(0, 0), a2, voffA);
;             PG8_WAIT_V(8); PG8_WAIT_L(0); PG8_BAR; PG8_MMA(1, 0, At, B0); PG8_MMA(1, 1, At, B1); PG8_BAR; PG8_SCHED;
.LBB0_1645:
	s_waitcnt lgkmcnt(0)
	ds_read_b128 v[154:157], v182
	ds_read_b128 v[158:161], v182 offset:1024
	ds_read_b128 v[162:165], v182 offset:2048
	ds_read_b128 v[166:169], v182 offset:3072
	ds_read_b128 v[170:173], v183
	ds_read_b128 v[174:177], v183 offset:1024
	ds_read_b128 v[188:191], v183 offset:2048
	ds_read_b128 v[192:195], v183 offset:3072
	s_add_u32 s2, s8, 0xfffc0080
	s_addc_u32 s3, s9, -1
	s_cmp_eq_u32 vcc_lo, 12
	s_cselect_b32 s79, s7, s3
	s_cselect_b32 s78, s67, s2
	s_cselect_b32 s77, s69, s97
	s_cselect_b32 s76, s71, s96
	s_add_i32 m0, s83, 0xc000
	ds_read_b128 v[196:199], v184
	ds_read_b128 v[200:203], v184 offset:1024
	ds_read_b128 v[204:207], v184 offset:2048
	ds_read_b128 v[208:211], v184 offset:3072
	ds_read_b128 v[212:215], v184 offset:4096
	ds_read_b128 v[216:219], v184 offset:5120
	ds_read_b128 v[220:223], v184 offset:6144
	ds_read_b128 v[224:227], v184 offset:7168
	global_load_lds_dwordx4 v146, s[8:9]
	s_add_i32 m0, s83, 0xe000
	s_nop 0
	global_load_lds_dwordx4 v148, s[8:9]
	s_waitcnt vmcnt(8)
	s_waitcnt lgkmcnt(0)
	s_barrier
	s_setprio 0
	s_waitcnt lgkmcnt(0)
	v_mfma_f32_16x16x32_bf16 v[124:127], v[154:157], v[196:199], v[124:127]
	v_mfma_f32_16x16x32_bf16 v[120:123], v[162:165], v[196:199], v[120:123]
	v_mfma_f32_16x16x32_bf16 v[108:111], v[154:157], v[204:207], v[108:111]
	v_mfma_f32_16x16x32_bf16 v[104:107], v[162:165], v[204:207], v[104:107]
	v_mfma_f32_16x16x32_bf16 v[92:95], v[154:157], v[212:215], v[92:95]
	v_mfma_f32_16x16x32_bf16 v[88:91], v[162:165], v[212:215], v[88:91]
	v_mfma_f32_16x16x32_bf16 v[76:79], v[154:157], v[220:223], v[76:79]
	v_mfma_f32_16x16x32_bf16 v[72:75], v[162:165], v[220:223], v[72:75]
	v_mfma_f32_16x16x32_bf16 v[124:127], v[158:161], v[200:203], v[124:127]
	v_mfma_f32_16x16x32_bf16 v[120:123], v[166:169], v[200:203], v[120:123]
	v_mfma_f32_16x16x32_bf16 v[108:111], v[158:161], v[208:211], v[108:111]
	v_mfma_f32_16x16x32_bf16 v[104:107], v[166:169], v[208:211], v[104:107]
	v_mfma_f32_16x16x32_bf16 v[92:95], v[158:161], v[216:219], v[92:95]
	v_mfma_f32_16x16x32_bf16 v[88:91], v[166:169], v[216:219], v[88:91]
	v_mfma_f32_16x16x32_bf16 v[76:79], v[158:161], v[224:227], v[76:79]
	v_mfma_f32_16x16x32_bf16 v[72:75], v[166:169], v[224:227], v[72:75]
	s_setprio 1
	s_setprio 0
	v_mfma_f32_16x16x32_bf16 v[116:119], v[170:173], v[196:199], v[116:119]
	v_mfma_f32_16x16x32_bf16 v[112:115], v[188:191], v[196:199], v[112:115]
	v_mfma_f32_16x16x32_bf16 v[100:103], v[170:173], v[204:207], v[100:103]
	v_mfma_f32_16x16x32_bf16 v[96:99], v[188:191], v[204:207], v[96:99]
	v_mfma_f32_16x16x32_bf16 v[84:87], v[170:173], v[212:215], v[84:87]
	v_mfma_f32_16x16x32_bf16 v[80:83], v[188:191], v[212:215], v[80:83]
	v_mfma_f32_16x16x32_bf16 v[68:71], v[170:173], v[220:223], v[68:71]
	v_mfma_f32_16x16x32_bf16 v[64:67], v[188:191], v[220:223], v[64:67]
	v_mfma_f32_16x16x32_bf16 v[116:119], v[174:177], v[200:203], v[116:119]
	v_mfma_f32_16x16x32_bf16 v[112:115], v[192:195], v[200:203], v[112:115]
	v_mfma_f32_16x16x32_bf16 v[100:103], v[174:177], v[208:211], v[100:103]
	v_mfma_f32_16x16x32_bf16 v[96:99], v[192:195], v[208:211], v[96:99]
	v_mfma_f32_16x16x32_bf16 v[84:87], v[174:177], v[216:219], v[84:87]
	v_mfma_f32_16x16x32_bf16 v[80:83], v[192:195], v[216:219], v[80:83]
	v_mfma_f32_16x16x32_bf16 v[68:71], v[174:177], v[224:227], v[68:71]
	v_mfma_f32_16x16x32_bf16 v[64:67], v[192:195], v[224:227], v[64:67]
	s_setprio 1
	s_barrier
	s_add_i32 s2, s91, s82
	s_mov_b32 m0, s2
	ds_read_b128 v[196:199], v184 offset:16384
	ds_read_b128 v[200:203], v184 offset:17408
	ds_read_b128 v[204:207], v184 offset:18432
	ds_read_b128 v[208:211], v184 offset:19456
	ds_read_b128 v[212:215], v184 offset:20480
	ds_read_b128 v[216:219], v184 offset:21504
	ds_read_b128 v[220:223], v184 offset:22528
	ds_read_b128 v[224:227], v184 offset:23552
	global_load_lds_dwordx4 v130, s[76:77]
	s_add_i32 m0, s2, 0x2000
	s_add_u32 s2, s76, 0x40000
	s_addc_u32 s3, s77, 0
	s_add_i32 vcc_hi, s92, s82
	global_load_lds_dwordx4 v134, s[76:77]
	s_mov_b32 m0, vcc_hi
	s_nop 0
	global_load_lds_dwordx4 v130, s[2:3]
	s_add_i32 m0, vcc_hi, 0x2000
	s_nop 0
	global_load_lds_dwordx4 v134, s[2:3]
	s_mov_b32 m0, s83
	s_nop 0
	global_load_lds_dwordx4 v128, s[78:79]
	s_mov_b32 m0, s84
	s_nop 0
	global_load_lds_dwordx4 v132, s[78:79]
	s_waitcnt vmcnt(8)
	s_waitcnt lgkmcnt(0)
	s_barrier
	s_setprio 0
	s_waitcnt lgkmcnt(0)
	v_mfma_f32_16x16x32_bf16 v[60:63], v[154:157], v[196:199], v[60:63]
	v_mfma_f32_16x16x32_bf16 v[56:59], v[162:165], v[196:199], v[56:59]
	v_mfma_f32_16x16x32_bf16 v[44:47], v[154:157], v[204:207], v[44:47]
	v_mfma_f32_16x16x32_bf16 v[40:43], v[162:165], v[204:207], v[40:43]
	v_mfma_f32_16x16x32_bf16 v[28:31], v[154:157], v[212:215], v[28:31]
	v_mfma_f32_16x16x32_bf16 v[24:27], v[162:165], v[212:215], v[24:27]
	v_mfma_f32_16x16x32_bf16 v[12:15], v[154:157], v[220:223], v[12:15]
	v_mfma_f32_16x16x32_bf16 v[8:11], v[162:165], v[220:223], v[8:11]
	v_mfma_f32_16x16x32_bf16 v[60:63], v[158:161], v[200:203], v[60:63]
	v_mfma_f32_16x16x32_bf16 v[56:59], v[166:169], v[200:203], v[56:59]
	v_mfma_f32_16x16x32_bf16 v[44:47], v[158:161], v[208:211], v[44:47]
	v_mfma_f32_16x16x32_bf16 v[40:43], v[166:169], v[208:211], v[40:43]
	v_mfma_f32_16x16x32_bf16 v[28:31], v[158:161], v[216:219], v[28:31]
	v_mfma_f32_16x16x32_bf16 v[24:27], v[166:169], v[216:219], v[24:27]
	v_mfma_f32_16x16x32_bf16 v[12:15], v[158:161], v[224:227], v[12:15]
	v_mfma_f32_16x16x32_bf16 v[8:11], v[166:169], v[224:227], v[8:11]
	s_setprio 1
	s_setprio 0
	v_mfma_f32_16x16x32_bf16 v[52:55], v[170:173], v[196:199], v[52:55]
	v_mfma_f32_16x16x32_bf16 v[48:51], v[188:191], v[196:199], v[48:51]
	v_mfma_f32_16x16x32_bf16 v[36:39], v[170:173], v[204:207], v[36:39]
	v_mfma_f32_16x16x32_bf16 v[32:35], v[188:191], v[204:207], v[32:35]
	v_mfma_f32_16x16x32_bf16 v[20:23], v[170:173], v[212:215], v[20:23]
	v_mfma_f32_16x16x32_bf16 v[16:19], v[188:191], v[212:215], v[16:19]
	v_mfma_f32_16x16x32_bf16 v[4:7], v[170:173], v[220:223], v[4:7]
	v_mfma_f32_16x16x32_bf16 v[0:3], v[188:191], v[220:223], v[0:3]
	v_mfma_f32_16x16x32_bf16 v[52:55], v[174:177], v[200:203], v[52:55]
	v_mfma_f32_16x16x32_bf16 v[48:51], v[192:195], v[200:203], v[48:51]
	v_mfma_f32_16x16x32_bf16 v[36:39], v[174:177], v[208:211], v[36:39]
	v_mfma_f32_16x16x32_bf16 v[32:35], v[192:195], v[208:211], v[32:35]
	v_mfma_f32_16x16x32_bf16 v[20:23], v[174:177], v[216:219], v[20:23]
	v_mfma_f32_16x16x32_bf16 v[16:19], v[192:195], v[216:219], v[16:19]
	v_mfma_f32_16x16x32_bf16 v[4:7], v[174:177], v[224:227], v[4:7]
	v_mfma_f32_16x16x32_bf16 v[0:3], v[192:195], v[224:227], v[0:3]
	s_setprio 1
	s_barrier
; #define PG8_STAGE(bufoff, gbase, voff) do { _Pragma("unroll") for (int _i = 0; _i < 2; ++_i) \
;         __builtin_amdgcn_global_load_lds((const unsigned*)((const char*)(gbase) + (voff)[_i]), (PG8_LAS unsigned*)(lds + (bufoff) + ldsw + _i * 8192), 16, 0, 0); } while (0)
; #define PG8_LDA(dst, b, h) do { _Pragma("unroll") for (int m = 0; m < 4; ++m) _Pragma("unroll") for (int k = 0; k < 2; ++k) dst[m][k] = *(const PG8_LAS bf16x8*)(lds + PG8_SA(b, h) + aoff + m * 2048 + k * 1024); } while (0)
; #define PG8_LDB(dst, b, h) do { _Pragma("unroll") for (int n = 0; n < 2; ++n) _Pragma("unroll") for (int k = 0; k < 2; ++k) dst[n][k] = *(const PG8_LAS bf16x8*)(lds + PG8_SB(b, h) + boff + n * 2048 + k * 1024); } while (0)
; #define PG8_MMA(ai, bj, At, Bt) do { __builtin_amdgcn_s_setprio(1); _Pragma("unroll") for (int m = 0; m < 4; ++m) _Pragma("unroll") for (int n = 0; n < 2; ++n) _Pragma("unroll") for (int k = 0; k < 2; ++k) \
;         acc[ai][bj][m][n] = __builtin_amdgcn_mfma_f32_16x16x32_bf16(Bt[n][k], At[m][k], acc[ai][bj][m][n], 0, 0, 0); __builtin_amdgcn_s_setprio(0); } while (0)
; #define PG8_WAIT_V(n) asm volatile("s_waitcnt vmcnt(" #n ")" ::: "memory")
; #define PG8_WAIT_L(n) asm volatile("s_waitcnt lgkmcnt(" #n ")" ::: "memory")
; #define PG8_BAR __builtin_amdgcn_s_barrier()
; #define PG8_SCHED __builtin_amdgcn_sched_barrier(0)
; template <class Epi, class Sched, bool ALIGN_EPI = false, bool SP2 = false>
; __device__ __forceinline__ void gemm_phase(PG8_LAS unsigned char* lds, const Gemm g, const Sched& S, const Epi& E, int wv) {
;     ...
;             PG8_LDB(B0, 1, 0); PG8_LDB(B1, 1, 1); PG8_SCHED; PG8_LDA(At, 1, 0); PG8_STAGE(PG8_SA(0, 1), a2 + hstepA, voffA);
;             PG8_WAIT_V(8); PG8_WAIT_L(0); PG8_BAR; PG8_MMA(0, 0, At, B0); PG8_MMA(0, 1, At, B1); PG8_BAR; PG8_SCHED;
;             PG8_LDA(At, 1, 1); PG8_STAGE(PG8_SB(1, 0), b3, voffB); PG8_STAGE(PG8_SB(1, 1), b3 + hstepB, voffB); PG8_STAGE(PG8_SA(1, 0), a3, voffA);
;             PG8_WAIT_V(8); PG8_WAIT_L(0); PG8_BAR; PG8_MMA(1, 0, At, B0); PG8_MMA(1, 1, At, B1); PG8_BAR; PG8_SCHED;
;     ...
;         }
;         if constexpr (ALIGN_EPI) { if (wr == 0) PG8_BAR; }
	s_add_i32 vcc_hi, 0, 0x18000
	v_add_u32_e32 v136, vcc_hi, v178
	s_add_i32 s42, 0, 0x1c000
	ds_read_b128 v[154:157], v136
	ds_read_b128 v[158:161], v136 offset:1024
	ds_read_b128 v[162:165], v136 offset:2048
	ds_read_b128 v[166:169], v136 offset:3072
	v_add_u32_e32 v136, s42, v178
	ds_read_b128 v[170:173], v136
	ds_read_b128 v[174:177], v136 offset:1024
	ds_read_b128 v[188:191], v136 offset:2048
	ds_read_b128 v[192:195], v136 offset:3072
	s_add_u32 s2, s78, 0x40000
	s_addc_u32 s3, s79, 0
	s_mov_b32 m0, s85
	ds_read_b128 v[196:199], v184 offset:32768
	ds_read_b128 v[200:203], v184 offset:33792
	ds_read_b128 v[204:207], v184 offset:34816
	ds_read_b128 v[208:211], v184 offset:35840
	ds_read_b128 v[212:215], v184 offset:36864
	ds_read_b128 v[216:219], v184 offset:37888
	ds_read_b128 v[220:223], v184 offset:38912
	ds_read_b128 v[224:227], v184 offset:39936
	global_load_lds_dwordx4 v128, s[2:3]
	s_mov_b32 m0, s86
	s_nop 0
	global_load_lds_dwordx4 v132, s[2:3]
	s_waitcnt vmcnt(8)
	s_waitcnt lgkmcnt(0)
	s_barrier
	s_setprio 0
	s_waitcnt lgkmcnt(0)
	v_mfma_f32_16x16x32_bf16 v[124:127], v[154:157], v[196:199], v[124:127]
	v_mfma_f32_16x16x32_bf16 v[120:123], v[162:165], v[196:199], v[120:123]
	v_mfma_f32_16x16x32_bf16 v[108:111], v[154:157], v[204:207], v[108:111]
	v_mfma_f32_16x16x32_bf16 v[104:107], v[162:165], v[204:207], v[104:107]
	v_mfma_f32_16x16x32_bf16 v[92:95], v[154:157], v[212:215], v[92:95]
	v_mfma_f32_16x16x32_bf16 v[88:91], v[162:165], v[212:215], v[88:91]
	v_mfma_f32_16x16x32_bf16 v[76:79], v[154:157], v[220:223], v[76:79]
	v_mfma_f32_16x16x32_bf16 v[72:75], v[162:165], v[220:223], v[72:75]
	v_mfma_f32_16x16x32_bf16 v[124:127], v[158:161], v[200:203], v[124:127]
	v_mfma_f32_16x16x32_bf16 v[120:123], v[166:169], v[200:203], v[120:123]
	v_mfma_f32_16x16x32_bf16 v[108:111], v[158:161], v[208:211], v[108:111]
	v_mfma_f32_16x16x32_bf16 v[104:107], v[166:169], v[208:211], v[104:107]
	v_mfma_f32_16x16x32_bf16 v[92:95], v[158:161], v[216:219], v[92:95]
	v_mfma_f32_16x16x32_bf16 v[88:91], v[166:169], v[216:219], v[88:91]
	v_mfma_f32_16x16x32_bf16 v[76:79], v[158:161], v[224:227], v[76:79]
	v_mfma_f32_16x16x32_bf16 v[72:75], v[166:169], v[224:227], v[72:75]
	s_setprio 1
	s_setprio 0
	v_mfma_f32_16x16x32_bf16 v[116:119], v[170:173], v[196:199], v[116:119]
	v_mfma_f32_16x16x32_bf16 v[112:115], v[188:191], v[196:199], v[112:115]
	v_mfma_f32_16x16x32_bf16 v[100:103], v[170:173], v[204:207], v[100:103]
	v_mfma_f32_16x16x32_bf16 v[96:99], v[188:191], v[204:207], v[96:99]
	v_mfma_f32_16x16x32_bf16 v[84:87], v[170:173], v[212:215], v[84:87]
	v_mfma_f32_16x16x32_bf16 v[80:83], v[188:191], v[212:215], v[80:83]
	v_mfma_f32_16x16x32_bf16 v[68:71], v[170:173], v[220:223], v[68:71]
	v_mfma_f32_16x16x32_bf16 v[64:67], v[188:191], v[220:223], v[64:67]
	v_mfma_f32_16x16x32_bf16 v[116:119], v[174:177], v[200:203], v[116:119]
	v_mfma_f32_16x16x32_bf16 v[112:115], v[192:195], v[200:203], v[112:115]
	v_mfma_f32_16x16x32_bf16 v[100:103], v[174:177], v[208:211], v[100:103]
	v_mfma_f32_16x16x32_bf16 v[96:99], v[192:195], v[208:211], v[96:99]
	v_mfma_f32_16x16x32_bf16 v[84:87], v[174:177], v[216:219], v[84:87]
	v_mfma_f32_16x16x32_bf16 v[80:83], v[192:195], v[216:219], v[80:83]
	v_mfma_f32_16x16x32_bf16 v[68:71], v[174:177], v[224:227], v[68:71]
	v_mfma_f32_16x16x32_bf16 v[64:67], v[192:195], v[224:227], v[64:67]
	s_setprio 1
	s_barrier
	s_add_i32 s2, vcc_hi, s82
	s_add_u32 s98, s76, 0x80
	s_addc_u32 s99, s77, 0
	s_mov_b32 m0, s2
	ds_read_b128 v[196:199], v184 offset:49152
	ds_read_b128 v[200:203], v184 offset:50176
	ds_read_b128 v[204:207], v184 offset:51200
	ds_read_b128 v[208:211], v184 offset:52224
	ds_read_b128 v[212:215], v184 offset:53248
	ds_read_b128 v[216:219], v184 offset:54272
	ds_read_b128 v[220:223], v184 offset:55296
	ds_read_b128 v[224:227], v184 offset:56320
	global_load_lds_dwordx4 v130, s[98:99]
	s_add_i32 m0, s2, 0x2000
	s_add_u32 s2, s76, 0x40080
	s_addc_u32 s3, s77, 0
	s_add_i32 s42, s42, s82
	global_load_lds_dwordx4 v134, s[98:99]
	s_mov_b32 m0, s42
	s_nop 0
	global_load_lds_dwordx4 v130, s[2:3]
	s_add_i32 m0, s42, 0x2000
	s_nop 0
	global_load_lds_dwordx4 v134, s[2:3]
	s_add_u32 s100, s78, 0x80
	s_addc_u32 s101, s79, 0
	s_mov_b32 m0, s87
	s_nop 0
	global_load_lds_dwordx4 v128, s[100:101]
	s_mov_b32 m0, s88
	s_nop 0
	global_load_lds_dwordx4 v132, s[100:101]
	s_waitcnt vmcnt(8)
	s_waitcnt lgkmcnt(0)
	s_barrier
	s_setprio 0
	s_waitcnt lgkmcnt(0)
	v_mfma_f32_16x16x32_bf16 v[60:63], v[154:157], v[196:199], v[60:63]
	v_mfma_f32_16x16x32_bf16 v[56:59], v[162:165], v[196:199], v[56:59]
	v_mfma_f32_16x16x32_bf16 v[44:47], v[154:157], v[204:207], v[44:47]
	v_mfma_f32_16x16x32_bf16 v[40:43], v[162:165], v[204:207], v[40:43]
	v_mfma_f32_16x16x32_bf16 v[28:31], v[154:157], v[212:215], v[28:31]
	v_mfma_f32_16x16x32_bf16 v[24:27], v[162:165], v[212:215], v[24:27]
	v_mfma_f32_16x16x32_bf16 v[12:15], v[154:157], v[220:223], v[12:15]
	v_mfma_f32_16x16x32_bf16 v[8:11], v[162:165], v[220:223], v[8:11]
	v_mfma_f32_16x16x32_bf16 v[60:63], v[158:161], v[200:203], v[60:63]
	v_mfma_f32_16x16x32_bf16 v[56:59], v[166:169], v[200:203], v[56:59]
	v_mfma_f32_16x16x32_bf16 v[44:47], v[158:161], v[208:211], v[44:47]
	v_mfma_f32_16x16x32_bf16 v[40:43], v[166:169], v[208:211], v[40:43]
	v_mfma_f32_16x16x32_bf16 v[28:31], v[158:161], v[216:219], v[28:31]
	v_mfma_f32_16x16x32_bf16 v[24:27], v[166:169], v[216:219], v[24:27]
	v_mfma_f32_16x16x32_bf16 v[12:15], v[158:161], v[224:227], v[12:15]
	v_mfma_f32_16x16x32_bf16 v[8:11], v[166:169], v[224:227], v[8:11]
	s_setprio 1
	s_setprio 0
	v_mfma_f32_16x16x32_bf16 v[52:55], v[170:173], v[196:199], v[52:55]
	v_mfma_f32_16x16x32_bf16 v[48:51], v[188:191], v[196:199], v[48:51]
	v_mfma_f32_16x16x32_bf16 v[36:39], v[170:173], v[204:207], v[36:39]
	v_mfma_f32_16x16x32_bf16 v[32:35], v[188:191], v[204:207], v[32:35]
	v_mfma_f32_16x16x32_bf16 v[20:23], v[170:173], v[212:215], v[20:23]
	v_mfma_f32_16x16x32_bf16 v[16:19], v[188:191], v[212:215], v[16:19]
	v_mfma_f32_16x16x32_bf16 v[4:7], v[170:173], v[220:223], v[4:7]
	v_mfma_f32_16x16x32_bf16 v[0:3], v[188:191], v[220:223], v[0:3]
	v_mfma_f32_16x16x32_bf16 v[52:55], v[174:177], v[200:203], v[52:55]
	v_mfma_f32_16x16x32_bf16 v[48:51], v[192:195], v[200:203], v[48:51]
	v_mfma_f32_16x16x32_bf16 v[36:39], v[174:177], v[208:211], v[36:39]
	v_mfma_f32_16x16x32_bf16 v[32:35], v[192:195], v[208:211], v[32:35]
	v_mfma_f32_16x16x32_bf16 v[20:23], v[174:177], v[216:219], v[20:23]
	v_mfma_f32_16x16x32_bf16 v[16:19], v[192:195], v[216:219], v[16:19]
	v_mfma_f32_16x16x32_bf16 v[4:7], v[174:177], v[224:227], v[4:7]
	v_mfma_f32_16x16x32_bf16 v[0:3], v[192:195], v[224:227], v[0:3]
	s_setprio 1
	s_barrier
	s_add_i32 vcc_lo, vcc_lo, 2
	s_add_u32 s8, s8, 0x100
	s_addc_u32 s9, s9, 0
	s_add_u32 s96, s96, 0x100
	s_addc_u32 s97, s97, 0
	s_cmp_gt_u32 vcc_lo, 13
	s_cbranch_scc0 .LBB0_1645
	s_and_b64 vcc, exec, s[56:57]
	s_cbranch_vccz .LBB0_1648
	s_barrier

; #define PG8_STAGE(bufoff, gbase, voff) do { _Pragma("unroll") for (int _i = 0; _i < 2; ++_i) \
;         __builtin_amdgcn_global_load_lds((const unsigned*)((const char*)(gbase) + (voff)[_i]), (PG8_LAS unsigned*)(lds + (bufoff) + ldsw + _i * 8192), 16, 0, 0); } while (0)
; #define PG8_LDA(dst, b, h) do { _Pragma("unroll") for (int m = 0; m < 4; ++m) _Pragma("unroll") for (int k = 0; k < 2; ++k) dst[m][k] = *(const PG8_LAS bf16x8*)(lds + PG8_SA(b, h) + aoff + m * 2048 + k * 1024); } while (0)
; #define PG8_LDB(dst, b, h) do { _Pragma("unroll") for (int n = 0; n < 2; ++n) _Pragma("unroll") for (int k = 0; k < 2; ++k) dst[n][k] = *(const PG8_LAS bf16x8*)(lds + PG8_SB(b, h) + boff + n * 2048 + k * 1024); } while (0)
; #define PG8_MMA(ai, bj, At, Bt) do { __builtin_amdgcn_s_setprio(1); _Pragma("unroll") for (int m = 0; m < 4; ++m) _Pragma("unroll") for (int n = 0; n < 2; ++n) _Pragma("unroll") for (int k = 0; k < 2; ++k) \
;         acc[ai][bj][m][n] = __builtin_amdgcn_mfma_f32_16x16x32_bf16(Bt[n][k], At[m][k], acc[ai][bj][m][n], 0, 0, 0); __builtin_amdgcn_s_setprio(0); } while (0)
; #define PG8_WAIT_V(n) asm volatile("s_waitcnt vmcnt(" #n ")" ::: "memory")
; #define PG8_WAIT_L(n) asm volatile("s_waitcnt lgkmcnt(" #n ")" ::: "memory")
; template <class Epi, class Sched, bool ALIGN_EPI = false, bool SP2 = false>
; __device__ __forceinline__ void gemm_phase(PG8_LAS unsigned char* lds, const Gemm g, const Sched& S, const Epi& E, int wv) {
;     ...
;             const bool last = (t == nt - 2);
;             const char* a1 = cA + (size_t)(t + 1) * kstep;
;             const char* a2 = last ? nA : cA + (size_t)(t + 2) * kstep; const char* b2 = last ? nB : cB + (size_t)(t + 2) * kstep;
;             const char* a3 = a2 + kstep; const char* b3 = b2 + kstep;
;             if (last && has_next) S.a_ready(nxt);
;             if constexpr (SP2) {
;             PG8_LDB(B0, 0, 0); PG8_LDB(B1, 0, 1); PG8_SCHED; PG8_LDA(At, 0, 0); PG8_STAGE(PG8_SA(1, 1), a1 + hstepA, voffA);
;             PG8_WAIT_V(8); PG8_WAIT_L(0); PG8_BAR; PG8_MMA(0, 0, At, B0); PG8_MMA(0, 1, At, B1); PG8_BAR; PG8_SCHED;
;             PG8_LDA(At, 0, 1); PG8_STAGE(PG8_SB(0, 0), b2, voffB); PG8_STAGE(PG8_SB(0, 1), b2 + hstepB, voffB); PG8_STAGE(PG8_SA(0, 0), a2, voffA);
;             PG8_WAIT_V(8); PG8_WAIT_L(0); PG8_BAR; PG8_MMA(1, 0, At, B0); PG8_MMA(1, 1, At, B1); PG8_BAR; PG8_SCHED;
.LBB0_2016:
	ds_read_b128 v[144:147], v153
	ds_read_b128 v[156:159], v153 offset:1024
	ds_read_b128 v[160:163], v153 offset:2048
	ds_read_b128 v[164:167], v153 offset:3072
	ds_read_b128 v[168:171], v154
	ds_read_b128 v[172:175], v154 offset:1024
	ds_read_b128 v[176:179], v154 offset:2048
	ds_read_b128 v[180:183], v154 offset:3072
	s_add_u32 s0, s38, 0xfffc0080
	s_addc_u32 s1, s39, -1
	s_cmp_eq_u32 s62, 12
	s_cselect_b32 s43, s23, s1
	s_cselect_b32 s42, s29, s0
	s_cselect_b32 s41, s21, s59
	s_cselect_b32 s40, s57, s58
	s_add_i32 m0, s37, 0xc000
	ds_read_b128 v[184:187], v155
	ds_read_b128 v[188:191], v155 offset:1024
	ds_read_b128 v[192:195], v155 offset:2048
	ds_read_b128 v[196:199], v155 offset:3072
	ds_read_b128 v[200:203], v155 offset:4096
	ds_read_b128 v[204:207], v155 offset:5120
	ds_read_b128 v[208:211], v155 offset:6144
	ds_read_b128 v[212:215], v155 offset:7168
	global_load_lds_dwordx4 v136, s[38:39]
	s_add_i32 m0, s37, 0xe000
	s_nop 0
	global_load_lds_dwordx4 v138, s[38:39]
	s_waitcnt vmcnt(8)
	s_waitcnt lgkmcnt(0)
	s_barrier
	s_setprio 0
	s_waitcnt lgkmcnt(0)
	v_mfma_f32_16x16x32_bf16 v[124:127], v[144:147], v[184:187], v[124:127]
	v_mfma_f32_16x16x32_bf16 v[120:123], v[160:163], v[184:187], v[120:123]
	v_mfma_f32_16x16x32_bf16 v[108:111], v[144:147], v[192:195], v[108:111]
	v_mfma_f32_16x16x32_bf16 v[104:107], v[160:163], v[192:195], v[104:107]
	v_mfma_f32_16x16x32_bf16 v[92:95], v[144:147], v[200:203], v[92:95]
	v_mfma_f32_16x16x32_bf16 v[88:91], v[160:163], v[200:203], v[88:91]
	v_mfma_f32_16x16x32_bf16 v[76:79], v[144:147], v[208:211], v[76:79]
	v_mfma_f32_16x16x32_bf16 v[72:75], v[160:163], v[208:211], v[72:75]
	v_mfma_f32_16x16x32_bf16 v[124:127], v[156:159], v[188:191], v[124:127]
	v_mfma_f32_16x16x32_bf16 v[120:123], v[164:167], v[188:191], v[120:123]
	v_mfma_f32_16x16x32_bf16 v[108:111], v[156:159], v[196:199], v[108:111]
	v_mfma_f32_16x16x32_bf16 v[104:107], v[164:167], v[196:199], v[104:107]
	v_mfma_f32_16x16x32_bf16 v[92:95], v[156:159], v[204:207], v[92:95]
	v_mfma_f32_16x16x32_bf16 v[88:91], v[164:167], v[204:207], v[88:91]
	v_mfma_f32_16x16x32_bf16 v[76:79], v[156:159], v[212:215], v[76:79]
	v_mfma_f32_16x16x32_bf16 v[72:75], v[164:167], v[212:215], v[72:75]
	s_setprio 1
	s_setprio 0
	v_mfma_f32_16x16x32_bf16 v[116:119], v[168:171], v[184:187], v[116:119]
	v_mfma_f32_16x16x32_bf16 v[112:115], v[176:179], v[184:187], v[112:115]
	v_mfma_f32_16x16x32_bf16 v[100:103], v[168:171], v[192:195], v[100:103]
	v_mfma_f32_16x16x32_bf16 v[96:99], v[176:179], v[192:195], v[96:99]
	v_mfma_f32_16x16x32_bf16 v[84:87], v[168:171], v[200:203], v[84:87]
	v_mfma_f32_16x16x32_bf16 v[80:83], v[176:179], v[200:203], v[80:83]
	v_mfma_f32_16x16x32_bf16 v[68:71], v[168:171], v[208:211], v[68:71]
	v_mfma_f32_16x16x32_bf16 v[64:67], v[176:179], v[208:211], v[64:67]
	v_mfma_f32_16x16x32_bf16 v[116:119], v[172:175], v[188:191], v[116:119]
	v_mfma_f32_16x16x32_bf16 v[112:115], v[180:183], v[188:191], v[112:115]
	v_mfma_f32_16x16x32_bf16 v[100:103], v[172:175], v[196:199], v[100:103]
	v_mfma_f32_16x16x32_bf16 v[96:99], v[180:183], v[196:199], v[96:99]
	v_mfma_f32_16x16x32_bf16 v[84:87], v[172:175], v[204:207], v[84:87]
	v_mfma_f32_16x16x32_bf16 v[80:83], v[180:183], v[204:207], v[80:83]
	v_mfma_f32_16x16x32_bf16 v[68:71], v[172:175], v[212:215], v[68:71]
	v_mfma_f32_16x16x32_bf16 v[64:67], v[180:183], v[212:215], v[64:67]
	s_setprio 1
	s_barrier
	s_add_i32 s0, s55, s46
	s_mov_b32 m0, s0
	ds_read_b128 v[184:187], v155 offset:16384
	ds_read_b128 v[188:191], v155 offset:17408
	ds_read_b128 v[192:195], v155 offset:18432
	ds_read_b128 v[196:199], v155 offset:19456
	ds_read_b128 v[200:203], v155 offset:20480
	ds_read_b128 v[204:207], v155 offset:21504
	ds_read_b128 v[208:211], v155 offset:22528
	ds_read_b128 v[212:215], v155 offset:23552
	global_load_lds_dwordx4 v130, s[40:41]
	s_add_i32 m0, s0, 0x2000
	s_add_u32 s0, s40, 0x40000
	s_addc_u32 s1, s41, 0
	s_add_i32 s63, s56, s46
	global_load_lds_dwordx4 v134, s[40:41]
	s_mov_b32 m0, s63
	s_nop 0
	global_load_lds_dwordx4 v130, s[0:1]
	s_add_i32 m0, s63, 0x2000
	s_nop 0
	global_load_lds_dwordx4 v134, s[0:1]
	s_mov_b32 m0, s37
	s_nop 0
	global_load_lds_dwordx4 v128, s[42:43]
	s_mov_b32 m0, s47
	s_nop 0
	global_load_lds_dwordx4 v132, s[42:43]
	s_waitcnt vmcnt(8)
	s_waitcnt lgkmcnt(0)
	s_barrier
	s_setprio 0
	s_waitcnt lgkmcnt(0)
	v_mfma_f32_16x16x32_bf16 v[60:63], v[144:147], v[184:187], v[60:63]
	v_mfma_f32_16x16x32_bf16 v[56:59], v[160:163], v[184:187], v[56:59]
	v_mfma_f32_16x16x32_bf16 v[44:47], v[144:147], v[192:195], v[44:47]
	v_mfma_f32_16x16x32_bf16 v[40:43], v[160:163], v[192:195], v[40:43]
	v_mfma_f32_16x16x32_bf16 v[28:31], v[144:147], v[200:203], v[28:31]
	v_mfma_f32_16x16x32_bf16 v[24:27], v[160:163], v[200:203], v[24:27]
	v_mfma_f32_16x16x32_bf16 v[12:15], v[144:147], v[208:211], v[12:15]
	v_mfma_f32_16x16x32_bf16 v[8:11], v[160:163], v[208:211], v[8:11]
	v_mfma_f32_16x16x32_bf16 v[60:63], v[156:159], v[188:191], v[60:63]
	v_mfma_f32_16x16x32_bf16 v[56:59], v[164:167], v[188:191], v[56:59]
	v_mfma_f32_16x16x32_bf16 v[44:47], v[156:159], v[196:199], v[44:47]
	v_mfma_f32_16x16x32_bf16 v[40:43], v[164:167], v[196:199], v[40:43]
	v_mfma_f32_16x16x32_bf16 v[28:31], v[156:159], v[204:207], v[28:31]
	v_mfma_f32_16x16x32_bf16 v[24:27], v[164:167], v[204:207], v[24:27]
	v_mfma_f32_16x16x32_bf16 v[12:15], v[156:159], v[212:215], v[12:15]
	v_mfma_f32_16x16x32_bf16 v[8:11], v[164:167], v[212:215], v[8:11]
	s_setprio 1
	s_setprio 0
	v_mfma_f32_16x16x32_bf16 v[52:55], v[168:171], v[184:187], v[52:55]
	v_mfma_f32_16x16x32_bf16 v[48:51], v[176:179], v[184:187], v[48:51]
	v_mfma_f32_16x16x32_bf16 v[36:39], v[168:171], v[192:195], v[36:39]
	v_mfma_f32_16x16x32_bf16 v[32:35], v[176:179], v[192:195], v[32:35]
	v_mfma_f32_16x16x32_bf16 v[20:23], v[168:171], v[200:203], v[20:23]
	v_mfma_f32_16x16x32_bf16 v[16:19], v[176:179], v[200:203], v[16:19]
	v_mfma_f32_16x16x32_bf16 v[4:7], v[168:171], v[208:211], v[4:7]
	v_mfma_f32_16x16x32_bf16 v[0:3], v[176:179], v[208:211], v[0:3]
	v_mfma_f32_16x16x32_bf16 v[52:55], v[172:175], v[188:191], v[52:55]
	v_mfma_f32_16x16x32_bf16 v[48:51], v[180:183], v[188:191], v[48:51]
	v_mfma_f32_16x16x32_bf16 v[36:39], v[172:175], v[196:199], v[36:39]
	v_mfma_f32_16x16x32_bf16 v[32:35], v[180:183], v[196:199], v[32:35]
	v_mfma_f32_16x16x32_bf16 v[20:23], v[172:175], v[204:207], v[20:23]
	v_mfma_f32_16x16x32_bf16 v[16:19], v[180:183], v[204:207], v[16:19]
	v_mfma_f32_16x16x32_bf16 v[4:7], v[172:175], v[212:215], v[4:7]
	v_mfma_f32_16x16x32_bf16 v[0:3], v[180:183], v[212:215], v[0:3]
	s_setprio 1
	s_barrier
; #define PG8_STAGE(bufoff, gbase, voff) do { _Pragma("unroll") for (int _i = 0; _i < 2; ++_i) \
;         __builtin_amdgcn_global_load_lds((const unsigned*)((const char*)(gbase) + (voff)[_i]), (PG8_LAS unsigned*)(lds + (bufoff) + ldsw + _i * 8192), 16, 0, 0); } while (0)
; #define PG8_LDA(dst, b, h) do { _Pragma("unroll") for (int m = 0; m < 4; ++m) _Pragma("unroll") for (int k = 0; k < 2; ++k) dst[m][k] = *(const PG8_LAS bf16x8*)(lds + PG8_SA(b, h) + aoff + m * 2048 + k * 1024); } while (0)
; #define PG8_LDB(dst, b, h) do { _Pragma("unroll") for (int n = 0; n < 2; ++n) _Pragma("unroll") for (int k = 0; k < 2; ++k) dst[n][k] = *(const PG8_LAS bf16x8*)(lds + PG8_SB(b, h) + boff + n * 2048 + k * 1024); } while (0)
; #define PG8_MMA(ai, bj, At, Bt) do { __builtin_amdgcn_s_setprio(1); _Pragma("unroll") for (int m = 0; m < 4; ++m) _Pragma("unroll") for (int n = 0; n < 2; ++n) _Pragma("unroll") for (int k = 0; k < 2; ++k) \
;         acc[ai][bj][m][n] = __builtin_amdgcn_mfma_f32_16x16x32_bf16(Bt[n][k], At[m][k], acc[ai][bj][m][n], 0, 0, 0); __builtin_amdgcn_s_setprio(0); } while (0)
; #define PG8_WAIT_V(n) asm volatile("s_waitcnt vmcnt(" #n ")" ::: "memory")
; #define PG8_WAIT_L(n) asm volatile("s_waitcnt lgkmcnt(" #n ")" ::: "memory")
; #define PG8_BAR __builtin_amdgcn_s_barrier()
; #define PG8_SCHED __builtin_amdgcn_sched_barrier(0)
; template <class Epi, class Sched, bool ALIGN_EPI = false, bool SP2 = false>
; __device__ __forceinline__ void gemm_phase(PG8_LAS unsigned char* lds, const Gemm g, const Sched& S, const Epi& E, int wv) {
;     ...
;             PG8_LDB(B0, 1, 0); PG8_LDB(B1, 1, 1); PG8_SCHED; PG8_LDA(At, 1, 0); PG8_STAGE(PG8_SA(0, 1), a2 + hstepA, voffA);
;             PG8_WAIT_V(8); PG8_WAIT_L(0); PG8_BAR; PG8_MMA(0, 0, At, B0); PG8_MMA(0, 1, At, B1); PG8_BAR; PG8_SCHED;
;             PG8_LDA(At, 1, 1); PG8_STAGE(PG8_SB(1, 0), b3, voffB); PG8_STAGE(PG8_SB(1, 1), b3 + hstepB, voffB); PG8_STAGE(PG8_SA(1, 0), a3, voffA);
;             PG8_WAIT_V(8); PG8_WAIT_L(0); PG8_BAR; PG8_MMA(1, 0, At, B0); PG8_MMA(1, 1, At, B1); PG8_BAR; PG8_SCHED;
;     ...
;         }
;         if constexpr (ALIGN_EPI) { if (wr == 0) PG8_BAR; }
	s_add_i32 s63, 0, 0x18000
	s_add_i32 s64, 0, 0x1c000
	v_add_u32_e32 v164, s63, v149
	v_add_u32_e32 v180, s64, v149
	ds_read_b128 v[144:147], v164
	ds_read_b128 v[156:159], v164 offset:1024
	ds_read_b128 v[160:163], v164 offset:2048
	ds_read_b128 v[164:167], v164 offset:3072
	ds_read_b128 v[168:171], v180
	ds_read_b128 v[172:175], v180 offset:1024
	ds_read_b128 v[176:179], v180 offset:2048
	ds_read_b128 v[180:183], v180 offset:3072
	s_add_u32 s0, s42, 0x40000
	s_addc_u32 s1, s43, 0
	s_mov_b32 m0, s48
	ds_read_b128 v[184:187], v155 offset:32768
	ds_read_b128 v[188:191], v155 offset:33792
	ds_read_b128 v[192:195], v155 offset:34816
	ds_read_b128 v[196:199], v155 offset:35840
	ds_read_b128 v[200:203], v155 offset:36864
	ds_read_b128 v[204:207], v155 offset:37888
	ds_read_b128 v[208:211], v155 offset:38912
	ds_read_b128 v[212:215], v155 offset:39936
	global_load_lds_dwordx4 v128, s[0:1]
	s_mov_b32 m0, s49
	s_nop 0
	global_load_lds_dwordx4 v132, s[0:1]
	s_waitcnt vmcnt(8)
	s_waitcnt lgkmcnt(0)
	s_barrier
	s_setprio 0
	s_waitcnt lgkmcnt(0)
	v_mfma_f32_16x16x32_bf16 v[124:127], v[144:147], v[184:187], v[124:127]
	v_mfma_f32_16x16x32_bf16 v[120:123], v[160:163], v[184:187], v[120:123]
	v_mfma_f32_16x16x32_bf16 v[108:111], v[144:147], v[192:195], v[108:111]
	v_mfma_f32_16x16x32_bf16 v[104:107], v[160:163], v[192:195], v[104:107]
	v_mfma_f32_16x16x32_bf16 v[92:95], v[144:147], v[200:203], v[92:95]
	v_mfma_f32_16x16x32_bf16 v[88:91], v[160:163], v[200:203], v[88:91]
	v_mfma_f32_16x16x32_bf16 v[76:79], v[144:147], v[208:211], v[76:79]
	v_mfma_f32_16x16x32_bf16 v[72:75], v[160:163], v[208:211], v[72:75]
	v_mfma_f32_16x16x32_bf16 v[124:127], v[156:159], v[188:191], v[124:127]
	v_mfma_f32_16x16x32_bf16 v[120:123], v[164:167], v[188:191], v[120:123]
	v_mfma_f32_16x16x32_bf16 v[108:111], v[156:159], v[196:199], v[108:111]
	v_mfma_f32_16x16x32_bf16 v[104:107], v[164:167], v[196:199], v[104:107]
	v_mfma_f32_16x16x32_bf16 v[92:95], v[156:159], v[204:207], v[92:95]
	v_mfma_f32_16x16x32_bf16 v[88:91], v[164:167], v[204:207], v[88:91]
	v_mfma_f32_16x16x32_bf16 v[76:79], v[156:159], v[212:215], v[76:79]
	v_mfma_f32_16x16x32_bf16 v[72:75], v[164:167], v[212:215], v[72:75]
	s_setprio 1
	s_setprio 0
	v_mfma_f32_16x16x32_bf16 v[116:119], v[168:171], v[184:187], v[116:119]
	v_mfma_f32_16x16x32_bf16 v[112:115], v[176:179], v[184:187], v[112:115]
	v_mfma_f32_16x16x32_bf16 v[100:103], v[168:171], v[192:195], v[100:103]
	v_mfma_f32_16x16x32_bf16 v[96:99], v[176:179], v[192:195], v[96:99]
	v_mfma_f32_16x16x32_bf16 v[84:87], v[168:171], v[200:203], v[84:87]
	v_mfma_f32_16x16x32_bf16 v[80:83], v[176:179], v[200:203], v[80:83]
	v_mfma_f32_16x16x32_bf16 v[68:71], v[168:171], v[208:211], v[68:71]
	v_mfma_f32_16x16x32_bf16 v[64:67], v[176:179], v[208:211], v[64:67]
	v_mfma_f32_16x16x32_bf16 v[116:119], v[172:175], v[188:191], v[116:119]
	v_mfma_f32_16x16x32_bf16 v[112:115], v[180:183], v[188:191], v[112:115]
	v_mfma_f32_16x16x32_bf16 v[100:103], v[172:175], v[196:199], v[100:103]
	v_mfma_f32_16x16x32_bf16 v[96:99], v[180:183], v[196:199], v[96:99]
	v_mfma_f32_16x16x32_bf16 v[84:87], v[172:175], v[204:207], v[84:87]
	v_mfma_f32_16x16x32_bf16 v[80:83], v[180:183], v[204:207], v[80:83]
	v_mfma_f32_16x16x32_bf16 v[68:71], v[172:175], v[212:215], v[68:71]
	v_mfma_f32_16x16x32_bf16 v[64:67], v[180:183], v[212:215], v[64:67]
	s_setprio 1
	s_barrier
	s_add_i32 s0, s63, s46
	s_add_u32 s76, s40, 0x80
	s_addc_u32 s77, s41, 0
	s_mov_b32 m0, s0
	ds_read_b128 v[184:187], v155 offset:49152
	ds_read_b128 v[188:191], v155 offset:50176
	ds_read_b128 v[192:195], v155 offset:51200
	ds_read_b128 v[196:199], v155 offset:52224
	ds_read_b128 v[200:203], v155 offset:53248
	ds_read_b128 v[204:207], v155 offset:54272
	ds_read_b128 v[208:211], v155 offset:55296
	ds_read_b128 v[212:215], v155 offset:56320
	global_load_lds_dwordx4 v130, s[76:77]
	s_add_i32 m0, s0, 0x2000
	s_add_u32 s0, s40, 0x40080
	s_addc_u32 s1, s41, 0
	s_add_i32 s40, s64, s46
	global_load_lds_dwordx4 v134, s[76:77]
	s_mov_b32 m0, s40
	s_nop 0
	global_load_lds_dwordx4 v130, s[0:1]
	s_add_i32 m0, s40, 0x2000
	s_nop 0
	global_load_lds_dwordx4 v134, s[0:1]
	s_add_u32 s78, s42, 0x80
	s_addc_u32 s79, s43, 0
	s_mov_b32 m0, s51
	s_nop 0
	global_load_lds_dwordx4 v128, s[78:79]
	s_mov_b32 m0, s52
	s_nop 0
	global_load_lds_dwordx4 v132, s[78:79]
	s_waitcnt vmcnt(8)
	s_waitcnt lgkmcnt(0)
	s_barrier
	s_setprio 0
	s_waitcnt lgkmcnt(0)
	v_mfma_f32_16x16x32_bf16 v[60:63], v[144:147], v[184:187], v[60:63]
	v_mfma_f32_16x16x32_bf16 v[56:59], v[160:163], v[184:187], v[56:59]
	v_mfma_f32_16x16x32_bf16 v[44:47], v[144:147], v[192:195], v[44:47]
	v_mfma_f32_16x16x32_bf16 v[40:43], v[160:163], v[192:195], v[40:43]
	v_mfma_f32_16x16x32_bf16 v[28:31], v[144:147], v[200:203], v[28:31]
	v_mfma_f32_16x16x32_bf16 v[24:27], v[160:163], v[200:203], v[24:27]
	v_mfma_f32_16x16x32_bf16 v[12:15], v[144:147], v[208:211], v[12:15]
	v_mfma_f32_16x16x32_bf16 v[8:11], v[160:163], v[208:211], v[8:11]
	v_mfma_f32_16x16x32_bf16 v[60:63], v[156:159], v[188:191], v[60:63]
	v_mfma_f32_16x16x32_bf16 v[56:59], v[164:167], v[188:191], v[56:59]
	v_mfma_f32_16x16x32_bf16 v[44:47], v[156:159], v[196:199], v[44:47]
	v_mfma_f32_16x16x32_bf16 v[40:43], v[164:167], v[196:199], v[40:43]
	v_mfma_f32_16x16x32_bf16 v[28:31], v[156:159], v[204:207], v[28:31]
	v_mfma_f32_16x16x32_bf16 v[24:27], v[164:167], v[204:207], v[24:27]
	v_mfma_f32_16x16x32_bf16 v[12:15], v[156:159], v[212:215], v[12:15]
	v_mfma_f32_16x16x32_bf16 v[8:11], v[164:167], v[212:215], v[8:11]
	s_setprio 1
	s_setprio 0
	v_mfma_f32_16x16x32_bf16 v[52:55], v[168:171], v[184:187], v[52:55]
	v_mfma_f32_16x16x32_bf16 v[48:51], v[176:179], v[184:187], v[48:51]
	v_mfma_f32_16x16x32_bf16 v[36:39], v[168:171], v[192:195], v[36:39]
	v_mfma_f32_16x16x32_bf16 v[32:35], v[176:179], v[192:195], v[32:35]
	v_mfma_f32_16x16x32_bf16 v[20:23], v[168:171], v[200:203], v[20:23]
	v_mfma_f32_16x16x32_bf16 v[16:19], v[176:179], v[200:203], v[16:19]
	v_mfma_f32_16x16x32_bf16 v[4:7], v[168:171], v[208:211], v[4:7]
	v_mfma_f32_16x16x32_bf16 v[0:3], v[176:179], v[208:211], v[0:3]
	v_mfma_f32_16x16x32_bf16 v[52:55], v[172:175], v[188:191], v[52:55]
	v_mfma_f32_16x16x32_bf16 v[48:51], v[180:183], v[188:191], v[48:51]
	v_mfma_f32_16x16x32_bf16 v[36:39], v[172:175], v[196:199], v[36:39]
	v_mfma_f32_16x16x32_bf16 v[32:35], v[180:183], v[196:199], v[32:35]
	v_mfma_f32_16x16x32_bf16 v[20:23], v[172:175], v[204:207], v[20:23]
	v_mfma_f32_16x16x32_bf16 v[16:19], v[180:183], v[204:207], v[16:19]
	v_mfma_f32_16x16x32_bf16 v[4:7], v[172:175], v[212:215], v[4:7]
	v_mfma_f32_16x16x32_bf16 v[0:3], v[180:183], v[212:215], v[0:3]
	s_setprio 1
	s_barrier
	s_add_i32 s62, s62, 2
	s_add_u32 s38, s38, 0x100
	s_addc_u32 s39, s39, 0
	s_add_u32 s58, s58, 0x100
	s_addc_u32 s59, s59, 0
	s_cmp_gt_u32 s62, 13
	s_cbranch_scc0 .LBB0_2016
	s_and_b64 vcc, exec, s[18:19]
	s_cbranch_vccz .LBB0_2019
	s_barrier

; #define PG8_STAGE(bufoff, gbase, voff) do { _Pragma("unroll") for (int _i = 0; _i < 2; ++_i) \
;         __builtin_amdgcn_global_load_lds((const unsigned*)((const char*)(gbase) + (voff)[_i]), (PG8_LAS unsigned*)(lds + (bufoff) + ldsw + _i * 8192), 16, 0, 0); } while (0)
; #define PG8_LDA(dst, b, h) do { _Pragma("unroll") for (int m = 0; m < 4; ++m) _Pragma("unroll") for (int k = 0; k < 2; ++k) dst[m][k] = *(const PG8_LAS bf16x8*)(lds + PG8_SA(b, h) + aoff + m * 2048 + k * 1024); } while (0)
; #define PG8_LDB(dst, b, h) do { _Pragma("unroll") for (int n = 0; n < 2; ++n) _Pragma("unroll") for (int k = 0; k < 2; ++k) dst[n][k] = *(const PG8_LAS bf16x8*)(lds + PG8_SB(b, h) + boff + n * 2048 + k * 1024); } while (0)
; #define PG8_MMA(ai, bj, At, Bt) do { __builtin_amdgcn_s_setprio(1); _Pragma("unroll") for (int m = 0; m < 4; ++m) _Pragma("unroll") for (int n = 0; n < 2; ++n) _Pragma("unroll") for (int k = 0; k < 2; ++k) \
;         acc[ai][bj][m][n] = __builtin_amdgcn_mfma_f32_16x16x32_bf16(Bt[n][k], At[m][k], acc[ai][bj][m][n], 0, 0, 0); __builtin_amdgcn_s_setprio(0); } while (0)
; #define PG8_WAIT_V(n) asm volatile("s_waitcnt vmcnt(" #n ")" ::: "memory")
; #define PG8_WAIT_L(n) asm volatile("s_waitcnt lgkmcnt(" #n ")" ::: "memory")
; template <class Epi, class Sched, bool ALIGN_EPI = false, bool SP2 = false>
; __device__ __forceinline__ void gemm_phase(PG8_LAS unsigned char* lds, const Gemm g, const Sched& S, const Epi& E, int wv) {
;     ...
;             const bool last = (t == nt - 2);
;             const char* a1 = cA + (size_t)(t + 1) * kstep;
;             const char* a2 = last ? nA : cA + (size_t)(t + 2) * kstep; const char* b2 = last ? nB : cB + (size_t)(t + 2) * kstep;
;             const char* a3 = a2 + kstep; const char* b3 = b2 + kstep;
;             if (last && has_next) S.a_ready(nxt);
;             if constexpr (SP2) {
;             PG8_LDB(B0, 0, 0); PG8_LDB(B1, 0, 1); PG8_SCHED; PG8_LDA(At, 0, 0); PG8_STAGE(PG8_SA(1, 1), a1 + hstepA, voffA);
;             PG8_WAIT_V(8); PG8_WAIT_L(0); PG8_BAR; PG8_MMA(0, 0, At, B0); PG8_MMA(0, 1, At, B1); PG8_BAR; PG8_SCHED;
;             PG8_LDA(At, 0, 1); PG8_STAGE(PG8_SB(0, 0), b2, voffB); PG8_STAGE(PG8_SB(0, 1), b2 + hstepB, voffB); PG8_STAGE(PG8_SA(0, 0), a2, voffA);
;             PG8_WAIT_V(8); PG8_WAIT_L(0); PG8_BAR; PG8_MMA(1, 0, At, B0); PG8_MMA(1, 1, At, B1); PG8_BAR; PG8_SCHED;
.LBB0_2067:
	ds_read_b128 v[144:147], v155
	ds_read_b128 v[148:151], v155 offset:1024
	ds_read_b128 v[160:163], v155 offset:2048
	ds_read_b128 v[164:167], v155 offset:3072
	ds_read_b128 v[168:171], v156
	ds_read_b128 v[172:175], v156 offset:1024
	ds_read_b128 v[176:179], v156 offset:2048
	ds_read_b128 v[180:183], v156 offset:3072
	s_add_u32 s0, s42, 0xfffc0080
	s_addc_u32 s1, s43, -1
	s_cmp_eq_u32 s71, 12
	s_cselect_b32 s47, s37, s1
	s_cselect_b32 s46, s67, s0
	s_cselect_b32 s45, s29, s70
	s_cselect_b32 s44, s68, s69
	s_add_i32 m0, s52, 0xc000
	ds_read_b128 v[184:187], v157
	ds_read_b128 v[188:191], v157 offset:1024
	ds_read_b128 v[192:195], v157 offset:2048
	ds_read_b128 v[196:199], v157 offset:3072
	ds_read_b128 v[200:203], v157 offset:4096
	ds_read_b128 v[204:207], v157 offset:5120
	ds_read_b128 v[208:211], v157 offset:6144
	ds_read_b128 v[212:215], v157 offset:7168
	global_load_lds_dwordx4 v136, s[42:43]
	s_add_i32 m0, s52, 0xe000
	s_nop 0
	global_load_lds_dwordx4 v138, s[42:43]
	s_waitcnt vmcnt(8)
	s_waitcnt lgkmcnt(0)
	s_barrier
	s_setprio 0
	s_waitcnt lgkmcnt(0)
	v_mfma_f32_16x16x32_bf16 v[124:127], v[144:147], v[184:187], v[124:127]
	v_mfma_f32_16x16x32_bf16 v[120:123], v[160:163], v[184:187], v[120:123]
	v_mfma_f32_16x16x32_bf16 v[108:111], v[144:147], v[192:195], v[108:111]
	v_mfma_f32_16x16x32_bf16 v[104:107], v[160:163], v[192:195], v[104:107]
	v_mfma_f32_16x16x32_bf16 v[92:95], v[144:147], v[200:203], v[92:95]
	v_mfma_f32_16x16x32_bf16 v[88:91], v[160:163], v[200:203], v[88:91]
	v_mfma_f32_16x16x32_bf16 v[76:79], v[144:147], v[208:211], v[76:79]
	v_mfma_f32_16x16x32_bf16 v[72:75], v[160:163], v[208:211], v[72:75]
	v_mfma_f32_16x16x32_bf16 v[124:127], v[148:151], v[188:191], v[124:127]
	v_mfma_f32_16x16x32_bf16 v[120:123], v[164:167], v[188:191], v[120:123]
	v_mfma_f32_16x16x32_bf16 v[108:111], v[148:151], v[196:199], v[108:111]
	v_mfma_f32_16x16x32_bf16 v[104:107], v[164:167], v[196:199], v[104:107]
	v_mfma_f32_16x16x32_bf16 v[92:95], v[148:151], v[204:207], v[92:95]
	v_mfma_f32_16x16x32_bf16 v[88:91], v[164:167], v[204:207], v[88:91]
	v_mfma_f32_16x16x32_bf16 v[76:79], v[148:151], v[212:215], v[76:79]
	v_mfma_f32_16x16x32_bf16 v[72:75], v[164:167], v[212:215], v[72:75]
	s_setprio 1
	s_setprio 0
	v_mfma_f32_16x16x32_bf16 v[116:119], v[168:171], v[184:187], v[116:119]
	v_mfma_f32_16x16x32_bf16 v[112:115], v[176:179], v[184:187], v[112:115]
	v_mfma_f32_16x16x32_bf16 v[100:103], v[168:171], v[192:195], v[100:103]
	v_mfma_f32_16x16x32_bf16 v[96:99], v[176:179], v[192:195], v[96:99]
	v_mfma_f32_16x16x32_bf16 v[84:87], v[168:171], v[200:203], v[84:87]
	v_mfma_f32_16x16x32_bf16 v[80:83], v[176:179], v[200:203], v[80:83]
	v_mfma_f32_16x16x32_bf16 v[68:71], v[168:171], v[208:211], v[68:71]
	v_mfma_f32_16x16x32_bf16 v[64:67], v[176:179], v[208:211], v[64:67]
	v_mfma_f32_16x16x32_bf16 v[116:119], v[172:175], v[188:191], v[116:119]
	v_mfma_f32_16x16x32_bf16 v[112:115], v[180:183], v[188:191], v[112:115]
	v_mfma_f32_16x16x32_bf16 v[100:103], v[172:175], v[196:199], v[100:103]
	v_mfma_f32_16x16x32_bf16 v[96:99], v[180:183], v[196:199], v[96:99]
	v_mfma_f32_16x16x32_bf16 v[84:87], v[172:175], v[204:207], v[84:87]
	v_mfma_f32_16x16x32_bf16 v[80:83], v[180:183], v[204:207], v[80:83]
	v_mfma_f32_16x16x32_bf16 v[68:71], v[172:175], v[212:215], v[68:71]
	v_mfma_f32_16x16x32_bf16 v[64:67], v[180:183], v[212:215], v[64:67]
	s_setprio 1
	s_barrier
	s_add_i32 s0, s60, s51
	s_mov_b32 m0, s0
	ds_read_b128 v[184:187], v157 offset:16384
	ds_read_b128 v[188:191], v157 offset:17408
	ds_read_b128 v[192:195], v157 offset:18432
	ds_read_b128 v[196:199], v157 offset:19456
	ds_read_b128 v[200:203], v157 offset:20480
	ds_read_b128 v[204:207], v157 offset:21504
	ds_read_b128 v[208:211], v157 offset:22528
	ds_read_b128 v[212:215], v157 offset:23552
	global_load_lds_dwordx4 v130, s[44:45]
	s_add_i32 m0, s0, 0x2000
	s_add_u32 s0, s44, 0x40000
	s_addc_u32 s1, s45, 0
	s_add_i32 s72, s61, s51
	global_load_lds_dwordx4 v134, s[44:45]
	s_mov_b32 m0, s72
	s_nop 0
	global_load_lds_dwordx4 v130, s[0:1]
	s_add_i32 m0, s72, 0x2000
	s_nop 0
	global_load_lds_dwordx4 v134, s[0:1]
	s_mov_b32 m0, s52
	s_nop 0
	global_load_lds_dwordx4 v128, s[46:47]
	s_mov_b32 m0, s53
	s_nop 0
	global_load_lds_dwordx4 v132, s[46:47]
	s_waitcnt vmcnt(8)
	s_waitcnt lgkmcnt(0)
	s_barrier
	s_setprio 0
	s_waitcnt lgkmcnt(0)
	v_mfma_f32_16x16x32_bf16 v[60:63], v[144:147], v[184:187], v[60:63]
	v_mfma_f32_16x16x32_bf16 v[56:59], v[160:163], v[184:187], v[56:59]
	v_mfma_f32_16x16x32_bf16 v[44:47], v[144:147], v[192:195], v[44:47]
	v_mfma_f32_16x16x32_bf16 v[40:43], v[160:163], v[192:195], v[40:43]
	v_mfma_f32_16x16x32_bf16 v[28:31], v[144:147], v[200:203], v[28:31]
	v_mfma_f32_16x16x32_bf16 v[24:27], v[160:163], v[200:203], v[24:27]
	v_mfma_f32_16x16x32_bf16 v[12:15], v[144:147], v[208:211], v[12:15]
	v_mfma_f32_16x16x32_bf16 v[8:11], v[160:163], v[208:211], v[8:11]
	v_mfma_f32_16x16x32_bf16 v[60:63], v[148:151], v[188:191], v[60:63]
	v_mfma_f32_16x16x32_bf16 v[56:59], v[164:167], v[188:191], v[56:59]
	v_mfma_f32_16x16x32_bf16 v[44:47], v[148:151], v[196:199], v[44:47]
	v_mfma_f32_16x16x32_bf16 v[40:43], v[164:167], v[196:199], v[40:43]
	v_mfma_f32_16x16x32_bf16 v[28:31], v[148:151], v[204:207], v[28:31]
	v_mfma_f32_16x16x32_bf16 v[24:27], v[164:167], v[204:207], v[24:27]
	v_mfma_f32_16x16x32_bf16 v[12:15], v[148:151], v[212:215], v[12:15]
	v_mfma_f32_16x16x32_bf16 v[8:11], v[164:167], v[212:215], v[8:11]
	s_setprio 1
	s_setprio 0
	v_mfma_f32_16x16x32_bf16 v[52:55], v[168:171], v[184:187], v[52:55]
	v_mfma_f32_16x16x32_bf16 v[48:51], v[176:179], v[184:187], v[48:51]
	v_mfma_f32_16x16x32_bf16 v[36:39], v[168:171], v[192:195], v[36:39]
	v_mfma_f32_16x16x32_bf16 v[32:35], v[176:179], v[192:195], v[32:35]
	v_mfma_f32_16x16x32_bf16 v[20:23], v[168:171], v[200:203], v[20:23]
	v_mfma_f32_16x16x32_bf16 v[16:19], v[176:179], v[200:203], v[16:19]
	v_mfma_f32_16x16x32_bf16 v[4:7], v[168:171], v[208:211], v[4:7]
	v_mfma_f32_16x16x32_bf16 v[0:3], v[176:179], v[208:211], v[0:3]
	v_mfma_f32_16x16x32_bf16 v[52:55], v[172:175], v[188:191], v[52:55]
	v_mfma_f32_16x16x32_bf16 v[48:51], v[180:183], v[188:191], v[48:51]
	v_mfma_f32_16x16x32_bf16 v[36:39], v[172:175], v[196:199], v[36:39]
	v_mfma_f32_16x16x32_bf16 v[32:35], v[180:183], v[196:199], v[32:35]
	v_mfma_f32_16x16x32_bf16 v[20:23], v[172:175], v[204:207], v[20:23]
	v_mfma_f32_16x16x32_bf16 v[16:19], v[180:183], v[204:207], v[16:19]
	v_mfma_f32_16x16x32_bf16 v[4:7], v[172:175], v[212:215], v[4:7]
	v_mfma_f32_16x16x32_bf16 v[0:3], v[180:183], v[212:215], v[0:3]
	s_setprio 1
	s_barrier
; #define PG8_STAGE(bufoff, gbase, voff) do { _Pragma("unroll") for (int _i = 0; _i < 2; ++_i) \
;         __builtin_amdgcn_global_load_lds((const unsigned*)((const char*)(gbase) + (voff)[_i]), (PG8_LAS unsigned*)(lds + (bufoff) + ldsw + _i * 8192), 16, 0, 0); } while (0)
; #define PG8_LDA(dst, b, h) do { _Pragma("unroll") for (int m = 0; m < 4; ++m) _Pragma("unroll") for (int k = 0; k < 2; ++k) dst[m][k] = *(const PG8_LAS bf16x8*)(lds + PG8_SA(b, h) + aoff + m * 2048 + k * 1024); } while (0)
; #define PG8_LDB(dst, b, h) do { _Pragma("unroll") for (int n = 0; n < 2; ++n) _Pragma("unroll") for (int k = 0; k < 2; ++k) dst[n][k] = *(const PG8_LAS bf16x8*)(lds + PG8_SB(b, h) + boff + n * 2048 + k * 1024); } while (0)
; #define PG8_MMA(ai, bj, At, Bt) do { __builtin_amdgcn_s_setprio(1); _Pragma("unroll") for (int m = 0; m < 4; ++m) _Pragma("unroll") for (int n = 0; n < 2; ++n) _Pragma("unroll") for (int k = 0; k < 2; ++k) \
;         acc[ai][bj][m][n] = __builtin_amdgcn_mfma_f32_16x16x32_bf16(Bt[n][k], At[m][k], acc[ai][bj][m][n], 0, 0, 0); __builtin_amdgcn_s_setprio(0); } while (0)
; #define PG8_WAIT_V(n) asm volatile("s_waitcnt vmcnt(" #n ")" ::: "memory")
; #define PG8_WAIT_L(n) asm volatile("s_waitcnt lgkmcnt(" #n ")" ::: "memory")
; #define PG8_BAR __builtin_amdgcn_s_barrier()
; #define PG8_SCHED __builtin_amdgcn_sched_barrier(0)
; template <class Epi, class Sched, bool ALIGN_EPI = false, bool SP2 = false>
; __device__ __forceinline__ void gemm_phase(PG8_LAS unsigned char* lds, const Gemm g, const Sched& S, const Epi& E, int wv) {
;     ...
;             PG8_LDB(B0, 1, 0); PG8_LDB(B1, 1, 1); PG8_SCHED; PG8_LDA(At, 1, 0); PG8_STAGE(PG8_SA(0, 1), a2 + hstepA, voffA);
;             PG8_WAIT_V(8); PG8_WAIT_L(0); PG8_BAR; PG8_MMA(0, 0, At, B0); PG8_MMA(0, 1, At, B1); PG8_BAR; PG8_SCHED;
;             PG8_LDA(At, 1, 1); PG8_STAGE(PG8_SB(1, 0), b3, voffB); PG8_STAGE(PG8_SB(1, 1), b3 + hstepB, voffB); PG8_STAGE(PG8_SA(1, 0), a3, voffA);
;             PG8_WAIT_V(8); PG8_WAIT_L(0); PG8_BAR; PG8_MMA(1, 0, At, B0); PG8_MMA(1, 1, At, B1); PG8_BAR; PG8_SCHED;
;     ...
;         }
;         if constexpr (ALIGN_EPI) { if (wr == 0) PG8_BAR; }
	s_add_i32 s72, 0, 0x18000
	v_add_u32_e32 v159, s72, v153
	s_add_i32 s73, 0, 0x1c000
	ds_read_b128 v[144:147], v159
	ds_read_b128 v[148:151], v159 offset:1024
	ds_read_b128 v[160:163], v159 offset:2048
	ds_read_b128 v[164:167], v159 offset:3072
	v_add_u32_e32 v159, s73, v153
	ds_read_b128 v[168:171], v159
	ds_read_b128 v[172:175], v159 offset:1024
	ds_read_b128 v[176:179], v159 offset:2048
	ds_read_b128 v[180:183], v159 offset:3072
	s_add_u32 s0, s46, 0x40000
	s_addc_u32 s1, s47, 0
	s_mov_b32 m0, s54
	ds_read_b128 v[184:187], v157 offset:32768
	ds_read_b128 v[188:191], v157 offset:33792
	ds_read_b128 v[192:195], v157 offset:34816
	ds_read_b128 v[196:199], v157 offset:35840
	ds_read_b128 v[200:203], v157 offset:36864
	ds_read_b128 v[204:207], v157 offset:37888
	ds_read_b128 v[208:211], v157 offset:38912
	ds_read_b128 v[212:215], v157 offset:39936
	global_load_lds_dwordx4 v128, s[0:1]
	s_mov_b32 m0, s55
	s_nop 0
	global_load_lds_dwordx4 v132, s[0:1]
	s_waitcnt vmcnt(8)
	s_waitcnt lgkmcnt(0)
	s_barrier
	s_setprio 0
	s_waitcnt lgkmcnt(0)
	v_mfma_f32_16x16x32_bf16 v[124:127], v[144:147], v[184:187], v[124:127]
	v_mfma_f32_16x16x32_bf16 v[120:123], v[160:163], v[184:187], v[120:123]
	v_mfma_f32_16x16x32_bf16 v[108:111], v[144:147], v[192:195], v[108:111]
	v_mfma_f32_16x16x32_bf16 v[104:107], v[160:163], v[192:195], v[104:107]
	v_mfma_f32_16x16x32_bf16 v[92:95], v[144:147], v[200:203], v[92:95]
	v_mfma_f32_16x16x32_bf16 v[88:91], v[160:163], v[200:203], v[88:91]
	v_mfma_f32_16x16x32_bf16 v[76:79], v[144:147], v[208:211], v[76:79]
	v_mfma_f32_16x16x32_bf16 v[72:75], v[160:163], v[208:211], v[72:75]
	v_mfma_f32_16x16x32_bf16 v[124:127], v[148:151], v[188:191], v[124:127]
	v_mfma_f32_16x16x32_bf16 v[120:123], v[164:167], v[188:191], v[120:123]
	v_mfma_f32_16x16x32_bf16 v[108:111], v[148:151], v[196:199], v[108:111]
	v_mfma_f32_16x16x32_bf16 v[104:107], v[164:167], v[196:199], v[104:107]
	v_mfma_f32_16x16x32_bf16 v[92:95], v[148:151], v[204:207], v[92:95]
	v_mfma_f32_16x16x32_bf16 v[88:91], v[164:167], v[204:207], v[88:91]
	v_mfma_f32_16x16x32_bf16 v[76:79], v[148:151], v[212:215], v[76:79]
	v_mfma_f32_16x16x32_bf16 v[72:75], v[164:167], v[212:215], v[72:75]
	s_setprio 1
	s_setprio 0
	v_mfma_f32_16x16x32_bf16 v[116:119], v[168:171], v[184:187], v[116:119]
	v_mfma_f32_16x16x32_bf16 v[112:115], v[176:179], v[184:187], v[112:115]
	v_mfma_f32_16x16x32_bf16 v[100:103], v[168:171], v[192:195], v[100:103]
	v_mfma_f32_16x16x32_bf16 v[96:99], v[176:179], v[192:195], v[96:99]
	v_mfma_f32_16x16x32_bf16 v[84:87], v[168:171], v[200:203], v[84:87]
	v_mfma_f32_16x16x32_bf16 v[80:83], v[176:179], v[200:203], v[80:83]
	v_mfma_f32_16x16x32_bf16 v[68:71], v[168:171], v[208:211], v[68:71]
	v_mfma_f32_16x16x32_bf16 v[64:67], v[176:179], v[208:211], v[64:67]
	v_mfma_f32_16x16x32_bf16 v[116:119], v[172:175], v[188:191], v[116:119]
	v_mfma_f32_16x16x32_bf16 v[112:115], v[180:183], v[188:191], v[112:115]
	v_mfma_f32_16x16x32_bf16 v[100:103], v[172:175], v[196:199], v[100:103]
	v_mfma_f32_16x16x32_bf16 v[96:99], v[180:183], v[196:199], v[96:99]
	v_mfma_f32_16x16x32_bf16 v[84:87], v[172:175], v[204:207], v[84:87]
	v_mfma_f32_16x16x32_bf16 v[80:83], v[180:183], v[204:207], v[80:83]
	v_mfma_f32_16x16x32_bf16 v[68:71], v[172:175], v[212:215], v[68:71]
	v_mfma_f32_16x16x32_bf16 v[64:67], v[180:183], v[212:215], v[64:67]
	s_setprio 1
	s_barrier
	s_add_i32 s0, s72, s51
	s_add_u32 s76, s44, 0x80
	s_addc_u32 s77, s45, 0
	s_mov_b32 m0, s0
	ds_read_b128 v[184:187], v157 offset:49152
	ds_read_b128 v[188:191], v157 offset:50176
	ds_read_b128 v[192:195], v157 offset:51200
	ds_read_b128 v[196:199], v157 offset:52224
	ds_read_b128 v[200:203], v157 offset:53248
	ds_read_b128 v[204:207], v157 offset:54272
	ds_read_b128 v[208:211], v157 offset:55296
	ds_read_b128 v[212:215], v157 offset:56320
	global_load_lds_dwordx4 v130, s[76:77]
	s_add_i32 m0, s0, 0x2000
	s_add_u32 s0, s44, 0x40080
	s_addc_u32 s1, s45, 0
	s_add_i32 s44, s73, s51
	global_load_lds_dwordx4 v134, s[76:77]
	s_mov_b32 m0, s44
	s_nop 0
	global_load_lds_dwordx4 v130, s[0:1]
	s_add_i32 m0, s44, 0x2000
	s_nop 0
	global_load_lds_dwordx4 v134, s[0:1]
	s_add_u32 s78, s46, 0x80
	s_addc_u32 s79, s47, 0
	s_mov_b32 m0, s57
	s_nop 0
	global_load_lds_dwordx4 v128, s[78:79]
	s_mov_b32 m0, s58
	s_nop 0
	global_load_lds_dwordx4 v132, s[78:79]
	s_waitcnt vmcnt(8)
	s_waitcnt lgkmcnt(0)
	s_barrier
	s_setprio 0
	s_waitcnt lgkmcnt(0)
	v_mfma_f32_16x16x32_bf16 v[60:63], v[144:147], v[184:187], v[60:63]
	v_mfma_f32_16x16x32_bf16 v[56:59], v[160:163], v[184:187], v[56:59]
	v_mfma_f32_16x16x32_bf16 v[44:47], v[144:147], v[192:195], v[44:47]
	v_mfma_f32_16x16x32_bf16 v[40:43], v[160:163], v[192:195], v[40:43]
	v_mfma_f32_16x16x32_bf16 v[28:31], v[144:147], v[200:203], v[28:31]
	v_mfma_f32_16x16x32_bf16 v[24:27], v[160:163], v[200:203], v[24:27]
	v_mfma_f32_16x16x32_bf16 v[12:15], v[144:147], v[208:211], v[12:15]
	v_mfma_f32_16x16x32_bf16 v[8:11], v[160:163], v[208:211], v[8:11]
	v_mfma_f32_16x16x32_bf16 v[60:63], v[148:151], v[188:191], v[60:63]
	v_mfma_f32_16x16x32_bf16 v[56:59], v[164:167], v[188:191], v[56:59]
	v_mfma_f32_16x16x32_bf16 v[44:47], v[148:151], v[196:199], v[44:47]
	v_mfma_f32_16x16x32_bf16 v[40:43], v[164:167], v[196:199], v[40:43]
	v_mfma_f32_16x16x32_bf16 v[28:31], v[148:151], v[204:207], v[28:31]
	v_mfma_f32_16x16x32_bf16 v[24:27], v[164:167], v[204:207], v[24:27]
	v_mfma_f32_16x16x32_bf16 v[12:15], v[148:151], v[212:215], v[12:15]
	v_mfma_f32_16x16x32_bf16 v[8:11], v[164:167], v[212:215], v[8:11]
	s_setprio 1
	s_setprio 0
	v_mfma_f32_16x16x32_bf16 v[52:55], v[168:171], v[184:187], v[52:55]
	v_mfma_f32_16x16x32_bf16 v[48:51], v[176:179], v[184:187], v[48:51]
	v_mfma_f32_16x16x32_bf16 v[36:39], v[168:171], v[192:195], v[36:39]
	v_mfma_f32_16x16x32_bf16 v[32:35], v[176:179], v[192:195], v[32:35]
	v_mfma_f32_16x16x32_bf16 v[20:23], v[168:171], v[200:203], v[20:23]
	v_mfma_f32_16x16x32_bf16 v[16:19], v[176:179], v[200:203], v[16:19]
	v_mfma_f32_16x16x32_bf16 v[4:7], v[168:171], v[208:211], v[4:7]
	v_mfma_f32_16x16x32_bf16 v[0:3], v[176:179], v[208:211], v[0:3]
	v_mfma_f32_16x16x32_bf16 v[52:55], v[172:175], v[188:191], v[52:55]
	v_mfma_f32_16x16x32_bf16 v[48:51], v[180:183], v[188:191], v[48:51]
	v_mfma_f32_16x16x32_bf16 v[36:39], v[172:175], v[196:199], v[36:39]
	v_mfma_f32_16x16x32_bf16 v[32:35], v[180:183], v[196:199], v[32:35]
	v_mfma_f32_16x16x32_bf16 v[20:23], v[172:175], v[204:207], v[20:23]
	v_mfma_f32_16x16x32_bf16 v[16:19], v[180:183], v[204:207], v[16:19]
	v_mfma_f32_16x16x32_bf16 v[4:7], v[172:175], v[212:215], v[4:7]
	v_mfma_f32_16x16x32_bf16 v[0:3], v[180:183], v[212:215], v[0:3]
	s_setprio 1
	s_barrier
	s_add_i32 s71, s71, 2
	s_add_u32 s42, s42, 0x100
	s_addc_u32 s43, s43, 0
	s_add_u32 s69, s69, 0x100
	s_addc_u32 s70, s70, 0
	s_cmp_gt_u32 s71, 13
	s_cbranch_scc0 .LBB0_2067
	s_and_b64 vcc, exec, s[18:19]
	s_cbranch_vccz .LBB0_2070
	s_barrier

; #define PG8_STAGE(bufoff, gbase, voff) do { _Pragma("unroll") for (int _i = 0; _i < 2; ++_i) \
;         __builtin_amdgcn_global_load_lds((const unsigned*)((const char*)(gbase) + (voff)[_i]), (PG8_LAS unsigned*)(lds + (bufoff) + ldsw + _i * 8192), 16, 0, 0); } while (0)
; #define PG8_LDA(dst, b, h) do { _Pragma("unroll") for (int m = 0; m < 4; ++m) _Pragma("unroll") for (int k = 0; k < 2; ++k) dst[m][k] = *(const PG8_LAS bf16x8*)(lds + PG8_SA(b, h) + aoff + m * 2048 + k * 1024); } while (0)
; #define PG8_LDB(dst, b, h) do { _Pragma("unroll") for (int n = 0; n < 2; ++n) _Pragma("unroll") for (int k = 0; k < 2; ++k) dst[n][k] = *(const PG8_LAS bf16x8*)(lds + PG8_SB(b, h) + boff + n * 2048 + k * 1024); } while (0)
; #define PG8_MMA(ai, bj, At, Bt) do { __builtin_amdgcn_s_setprio(1); _Pragma("unroll") for (int m = 0; m < 4; ++m) _Pragma("unroll") for (int n = 0; n < 2; ++n) _Pragma("unroll") for (int k = 0; k < 2; ++k) \
;         acc[ai][bj][m][n] = __builtin_amdgcn_mfma_f32_16x16x32_bf16(Bt[n][k], At[m][k], acc[ai][bj][m][n], 0, 0, 0); __builtin_amdgcn_s_setprio(0); } while (0)
; #define PG8_WAIT_V(n) asm volatile("s_waitcnt vmcnt(" #n ")" ::: "memory")
; #define PG8_WAIT_L(n) asm volatile("s_waitcnt lgkmcnt(" #n ")" ::: "memory")
; template <class Epi, class Sched, bool ALIGN_EPI = false, bool SP2 = false>
; __device__ __forceinline__ void gemm_phase(PG8_LAS unsigned char* lds, const Gemm g, const Sched& S, const Epi& E, int wv) {
;     ...
;             const bool last = (t == nt - 2);
;             const char* a1 = cA + (size_t)(t + 1) * kstep;
;             const char* a2 = last ? nA : cA + (size_t)(t + 2) * kstep; const char* b2 = last ? nB : cB + (size_t)(t + 2) * kstep;
;             const char* a3 = a2 + kstep; const char* b3 = b2 + kstep;
;             if (last && has_next) S.a_ready(nxt);
;             if constexpr (SP2) {
;             PG8_LDB(B0, 0, 0); PG8_LDB(B1, 0, 1); PG8_SCHED; PG8_LDA(At, 0, 0); PG8_STAGE(PG8_SA(1, 1), a1 + hstepA, voffA);
;             PG8_WAIT_V(8); PG8_WAIT_L(0); PG8_BAR; PG8_MMA(0, 0, At, B0); PG8_MMA(0, 1, At, B1); PG8_BAR; PG8_SCHED;
;             PG8_LDA(At, 0, 1); PG8_STAGE(PG8_SB(0, 0), b2, voffB); PG8_STAGE(PG8_SB(0, 1), b2 + hstepB, voffB); PG8_STAGE(PG8_SA(0, 0), a2, voffA);
;             PG8_WAIT_V(8); PG8_WAIT_L(0); PG8_BAR; PG8_MMA(1, 0, At, B0); PG8_MMA(1, 1, At, B1); PG8_BAR; PG8_SCHED;
.LBB0_2102:
	ds_read_b128 v[144:147], v153
	ds_read_b128 v[156:159], v153 offset:1024
	ds_read_b128 v[160:163], v153 offset:2048
	ds_read_b128 v[164:167], v153 offset:3072
	ds_read_b128 v[168:171], v154
	ds_read_b128 v[172:175], v154 offset:1024
	ds_read_b128 v[176:179], v154 offset:2048
	ds_read_b128 v[180:183], v154 offset:3072
	s_add_u32 s38, s36, 0xfff00080
	s_addc_u32 s39, s37, -1
	s_cmp_eq_u32 s59, 60
	s_cselect_b32 s41, s23, s39
	s_cselect_b32 s40, s55, s38
	s_cselect_b32 s39, s21, s58
	s_cselect_b32 s38, s56, s57
	s_add_i32 m0, s29, 0xc000
	ds_read_b128 v[184:187], v155
	ds_read_b128 v[188:191], v155 offset:1024
	ds_read_b128 v[192:195], v155 offset:2048
	ds_read_b128 v[196:199], v155 offset:3072
	ds_read_b128 v[200:203], v155 offset:4096
	ds_read_b128 v[204:207], v155 offset:5120
	ds_read_b128 v[208:211], v155 offset:6144
	ds_read_b128 v[212:215], v155 offset:7168
	global_load_lds_dwordx4 v136, s[36:37]
	s_add_i32 m0, s29, 0xe000
	s_nop 0
	global_load_lds_dwordx4 v138, s[36:37]
	s_waitcnt vmcnt(8)
	s_waitcnt lgkmcnt(0)
	s_barrier
	s_setprio 0
	s_waitcnt lgkmcnt(0)
	v_mfma_f32_16x16x32_bf16 v[124:127], v[144:147], v[184:187], v[124:127]
	v_mfma_f32_16x16x32_bf16 v[120:123], v[160:163], v[184:187], v[120:123]
	v_mfma_f32_16x16x32_bf16 v[108:111], v[144:147], v[192:195], v[108:111]
	v_mfma_f32_16x16x32_bf16 v[104:107], v[160:163], v[192:195], v[104:107]
	v_mfma_f32_16x16x32_bf16 v[92:95], v[144:147], v[200:203], v[92:95]
	v_mfma_f32_16x16x32_bf16 v[88:91], v[160:163], v[200:203], v[88:91]
	v_mfma_f32_16x16x32_bf16 v[76:79], v[144:147], v[208:211], v[76:79]
	v_mfma_f32_16x16x32_bf16 v[72:75], v[160:163], v[208:211], v[72:75]
	v_mfma_f32_16x16x32_bf16 v[124:127], v[156:159], v[188:191], v[124:127]
	v_mfma_f32_16x16x32_bf16 v[120:123], v[164:167], v[188:191], v[120:123]
	v_mfma_f32_16x16x32_bf16 v[108:111], v[156:159], v[196:199], v[108:111]
	v_mfma_f32_16x16x32_bf16 v[104:107], v[164:167], v[196:199], v[104:107]
	v_mfma_f32_16x16x32_bf16 v[92:95], v[156:159], v[204:207], v[92:95]
	v_mfma_f32_16x16x32_bf16 v[88:91], v[164:167], v[204:207], v[88:91]
	v_mfma_f32_16x16x32_bf16 v[76:79], v[156:159], v[212:215], v[76:79]
	v_mfma_f32_16x16x32_bf16 v[72:75], v[164:167], v[212:215], v[72:75]
	s_setprio 1
	s_setprio 0
	v_mfma_f32_16x16x32_bf16 v[116:119], v[168:171], v[184:187], v[116:119]
	v_mfma_f32_16x16x32_bf16 v[112:115], v[176:179], v[184:187], v[112:115]
	v_mfma_f32_16x16x32_bf16 v[100:103], v[168:171], v[192:195], v[100:103]
	v_mfma_f32_16x16x32_bf16 v[96:99], v[176:179], v[192:195], v[96:99]
	v_mfma_f32_16x16x32_bf16 v[84:87], v[168:171], v[200:203], v[84:87]
	v_mfma_f32_16x16x32_bf16 v[80:83], v[176:179], v[200:203], v[80:83]
	v_mfma_f32_16x16x32_bf16 v[68:71], v[168:171], v[208:211], v[68:71]
	v_mfma_f32_16x16x32_bf16 v[64:67], v[176:179], v[208:211], v[64:67]
	v_mfma_f32_16x16x32_bf16 v[116:119], v[172:175], v[188:191], v[116:119]
	v_mfma_f32_16x16x32_bf16 v[112:115], v[180:183], v[188:191], v[112:115]
	v_mfma_f32_16x16x32_bf16 v[100:103], v[172:175], v[196:199], v[100:103]
	v_mfma_f32_16x16x32_bf16 v[96:99], v[180:183], v[196:199], v[96:99]
	v_mfma_f32_16x16x32_bf16 v[84:87], v[172:175], v[204:207], v[84:87]
	v_mfma_f32_16x16x32_bf16 v[80:83], v[180:183], v[204:207], v[80:83]
	v_mfma_f32_16x16x32_bf16 v[68:71], v[172:175], v[212:215], v[68:71]
	v_mfma_f32_16x16x32_bf16 v[64:67], v[180:183], v[212:215], v[64:67]
	s_setprio 1
	s_barrier
	s_add_i32 s60, s52, s44
	s_mov_b32 m0, s60
	ds_read_b128 v[184:187], v155 offset:16384
	ds_read_b128 v[188:191], v155 offset:17408
	ds_read_b128 v[192:195], v155 offset:18432
	ds_read_b128 v[196:199], v155 offset:19456
	ds_read_b128 v[200:203], v155 offset:20480
	ds_read_b128 v[204:207], v155 offset:21504
	ds_read_b128 v[208:211], v155 offset:22528
	ds_read_b128 v[212:215], v155 offset:23552
	global_load_lds_dwordx4 v130, s[38:39]
	s_add_i32 m0, s60, 0x2000
	s_add_u32 s60, s38, 0x100000
	s_addc_u32 s61, s39, 0
	s_add_i32 s62, s53, s44
	global_load_lds_dwordx4 v134, s[38:39]
	s_mov_b32 m0, s62
	s_add_u32 s82, s40, 0x80
	s_addc_u32 s83, s41, 0
	global_load_lds_dwordx4 v130, s[60:61]
	s_add_i32 m0, s62, 0x2000
	s_nop 0
	global_load_lds_dwordx4 v134, s[60:61]
	s_mov_b32 m0, s29
	s_nop 0
	global_load_lds_dwordx4 v128, s[40:41]
	s_mov_b32 m0, s45
	s_nop 0
	global_load_lds_dwordx4 v132, s[40:41]
	s_waitcnt vmcnt(8)
	s_waitcnt lgkmcnt(0)
	s_barrier
	s_setprio 0
	s_waitcnt lgkmcnt(0)
	v_mfma_f32_16x16x32_bf16 v[60:63], v[144:147], v[184:187], v[60:63]
	v_mfma_f32_16x16x32_bf16 v[56:59], v[160:163], v[184:187], v[56:59]
	v_mfma_f32_16x16x32_bf16 v[44:47], v[144:147], v[192:195], v[44:47]
	v_mfma_f32_16x16x32_bf16 v[40:43], v[160:163], v[192:195], v[40:43]
	v_mfma_f32_16x16x32_bf16 v[28:31], v[144:147], v[200:203], v[28:31]
	v_mfma_f32_16x16x32_bf16 v[24:27], v[160:163], v[200:203], v[24:27]
	v_mfma_f32_16x16x32_bf16 v[12:15], v[144:147], v[208:211], v[12:15]
	v_mfma_f32_16x16x32_bf16 v[8:11], v[160:163], v[208:211], v[8:11]
	v_mfma_f32_16x16x32_bf16 v[60:63], v[156:159], v[188:191], v[60:63]
	v_mfma_f32_16x16x32_bf16 v[56:59], v[164:167], v[188:191], v[56:59]
	v_mfma_f32_16x16x32_bf16 v[44:47], v[156:159], v[196:199], v[44:47]
	v_mfma_f32_16x16x32_bf16 v[40:43], v[164:167], v[196:199], v[40:43]
	v_mfma_f32_16x16x32_bf16 v[28:31], v[156:159], v[204:207], v[28:31]
	v_mfma_f32_16x16x32_bf16 v[24:27], v[164:167], v[204:207], v[24:27]
	v_mfma_f32_16x16x32_bf16 v[12:15], v[156:159], v[212:215], v[12:15]
	v_mfma_f32_16x16x32_bf16 v[8:11], v[164:167], v[212:215], v[8:11]
	s_setprio 1
	s_setprio 0
	v_mfma_f32_16x16x32_bf16 v[52:55], v[168:171], v[184:187], v[52:55]
	v_mfma_f32_16x16x32_bf16 v[48:51], v[176:179], v[184:187], v[48:51]
	v_mfma_f32_16x16x32_bf16 v[36:39], v[168:171], v[192:195], v[36:39]
	v_mfma_f32_16x16x32_bf16 v[32:35], v[176:179], v[192:195], v[32:35]
	v_mfma_f32_16x16x32_bf16 v[20:23], v[168:171], v[200:203], v[20:23]
	v_mfma_f32_16x16x32_bf16 v[16:19], v[176:179], v[200:203], v[16:19]
	v_mfma_f32_16x16x32_bf16 v[4:7], v[168:171], v[208:211], v[4:7]
	v_mfma_f32_16x16x32_bf16 v[0:3], v[176:179], v[208:211], v[0:3]
	v_mfma_f32_16x16x32_bf16 v[52:55], v[172:175], v[188:191], v[52:55]
	v_mfma_f32_16x16x32_bf16 v[48:51], v[180:183], v[188:191], v[48:51]
	v_mfma_f32_16x16x32_bf16 v[36:39], v[172:175], v[196:199], v[36:39]
	v_mfma_f32_16x16x32_bf16 v[32:35], v[180:183], v[196:199], v[32:35]
	v_mfma_f32_16x16x32_bf16 v[20:23], v[172:175], v[204:207], v[20:23]
	v_mfma_f32_16x16x32_bf16 v[16:19], v[180:183], v[204:207], v[16:19]
	v_mfma_f32_16x16x32_bf16 v[4:7], v[172:175], v[212:215], v[4:7]
	v_mfma_f32_16x16x32_bf16 v[0:3], v[180:183], v[212:215], v[0:3]
	s_setprio 1
	s_barrier
; #define PG8_STAGE(bufoff, gbase, voff) do { _Pragma("unroll") for (int _i = 0; _i < 2; ++_i) \
;         __builtin_amdgcn_global_load_lds((const unsigned*)((const char*)(gbase) + (voff)[_i]), (PG8_LAS unsigned*)(lds + (bufoff) + ldsw + _i * 8192), 16, 0, 0); } while (0)
; #define PG8_LDA(dst, b, h) do { _Pragma("unroll") for (int m = 0; m < 4; ++m) _Pragma("unroll") for (int k = 0; k < 2; ++k) dst[m][k] = *(const PG8_LAS bf16x8*)(lds + PG8_SA(b, h) + aoff + m * 2048 + k * 1024); } while (0)
; #define PG8_LDB(dst, b, h) do { _Pragma("unroll") for (int n = 0; n < 2; ++n) _Pragma("unroll") for (int k = 0; k < 2; ++k) dst[n][k] = *(const PG8_LAS bf16x8*)(lds + PG8_SB(b, h) + boff + n * 2048 + k * 1024); } while (0)
; #define PG8_MMA(ai, bj, At, Bt) do { __builtin_amdgcn_s_setprio(1); _Pragma("unroll") for (int m = 0; m < 4; ++m) _Pragma("unroll") for (int n = 0; n < 2; ++n) _Pragma("unroll") for (int k = 0; k < 2; ++k) \
;         acc[ai][bj][m][n] = __builtin_amdgcn_mfma_f32_16x16x32_bf16(Bt[n][k], At[m][k], acc[ai][bj][m][n], 0, 0, 0); __builtin_amdgcn_s_setprio(0); } while (0)
; #define PG8_WAIT_V(n) asm volatile("s_waitcnt vmcnt(" #n ")" ::: "memory")
; #define PG8_WAIT_L(n) asm volatile("s_waitcnt lgkmcnt(" #n ")" ::: "memory")
; #define PG8_BAR __builtin_amdgcn_s_barrier()
; #define PG8_SCHED __builtin_amdgcn_sched_barrier(0)
; template <class Epi, class Sched, bool ALIGN_EPI = false, bool SP2 = false>
; __device__ __forceinline__ void gemm_phase(PG8_LAS unsigned char* lds, const Gemm g, const Sched& S, const Epi& E, int wv) {
;     ...
;             PG8_LDB(B0, 1, 0); PG8_LDB(B1, 1, 1); PG8_SCHED; PG8_LDA(At, 1, 0); PG8_STAGE(PG8_SA(0, 1), a2 + hstepA, voffA);
;             PG8_WAIT_V(8); PG8_WAIT_L(0); PG8_BAR; PG8_MMA(0, 0, At, B0); PG8_MMA(0, 1, At, B1); PG8_BAR; PG8_SCHED;
;             PG8_LDA(At, 1, 1); PG8_STAGE(PG8_SB(1, 0), b3, voffB); PG8_STAGE(PG8_SB(1, 1), b3 + hstepB, voffB); PG8_STAGE(PG8_SA(1, 0), a3, voffA);
;             PG8_WAIT_V(8); PG8_WAIT_L(0); PG8_BAR; PG8_MMA(1, 0, At, B0); PG8_MMA(1, 1, At, B1); PG8_BAR; PG8_SCHED;
;     ...
;         }
;         if constexpr (ALIGN_EPI) { if (wr == 0) PG8_BAR; }
	s_add_i32 s60, 0, 0x18000
	s_add_i32 s61, 0, 0x1c000
	v_add_u32_e32 v164, s60, v151
	v_add_u32_e32 v180, s61, v151
	ds_read_b128 v[144:147], v164
	ds_read_b128 v[156:159], v164 offset:1024
	ds_read_b128 v[160:163], v164 offset:2048
	ds_read_b128 v[164:167], v164 offset:3072
	ds_read_b128 v[168:171], v180
	ds_read_b128 v[172:175], v180 offset:1024
	ds_read_b128 v[176:179], v180 offset:2048
	ds_read_b128 v[180:183], v180 offset:3072
	s_add_u32 s40, s40, 0x100000
	s_addc_u32 s41, s41, 0
	s_mov_b32 m0, s46
	ds_read_b128 v[184:187], v155 offset:32768
	ds_read_b128 v[188:191], v155 offset:33792
	ds_read_b128 v[192:195], v155 offset:34816
	ds_read_b128 v[196:199], v155 offset:35840
	ds_read_b128 v[200:203], v155 offset:36864
	ds_read_b128 v[204:207], v155 offset:37888
	ds_read_b128 v[208:211], v155 offset:38912
	ds_read_b128 v[212:215], v155 offset:39936
	global_load_lds_dwordx4 v128, s[40:41]
	s_mov_b32 m0, s47
	s_nop 0
	global_load_lds_dwordx4 v132, s[40:41]
	s_waitcnt vmcnt(8)
	s_waitcnt lgkmcnt(0)
	s_barrier
	s_setprio 0
	s_waitcnt lgkmcnt(0)
	v_mfma_f32_16x16x32_bf16 v[124:127], v[144:147], v[184:187], v[124:127]
	v_mfma_f32_16x16x32_bf16 v[120:123], v[160:163], v[184:187], v[120:123]
	v_mfma_f32_16x16x32_bf16 v[108:111], v[144:147], v[192:195], v[108:111]
	v_mfma_f32_16x16x32_bf16 v[104:107], v[160:163], v[192:195], v[104:107]
	v_mfma_f32_16x16x32_bf16 v[92:95], v[144:147], v[200:203], v[92:95]
	v_mfma_f32_16x16x32_bf16 v[88:91], v[160:163], v[200:203], v[88:91]
	v_mfma_f32_16x16x32_bf16 v[76:79], v[144:147], v[208:211], v[76:79]
	v_mfma_f32_16x16x32_bf16 v[72:75], v[160:163], v[208:211], v[72:75]
	v_mfma_f32_16x16x32_bf16 v[124:127], v[156:159], v[188:191], v[124:127]
	v_mfma_f32_16x16x32_bf16 v[120:123], v[164:167], v[188:191], v[120:123]
	v_mfma_f32_16x16x32_bf16 v[108:111], v[156:159], v[196:199], v[108:111]
	v_mfma_f32_16x16x32_bf16 v[104:107], v[164:167], v[196:199], v[104:107]
	v_mfma_f32_16x16x32_bf16 v[92:95], v[156:159], v[204:207], v[92:95]
	v_mfma_f32_16x16x32_bf16 v[88:91], v[164:167], v[204:207], v[88:91]
	v_mfma_f32_16x16x32_bf16 v[76:79], v[156:159], v[212:215], v[76:79]
	v_mfma_f32_16x16x32_bf16 v[72:75], v[164:167], v[212:215], v[72:75]
	s_setprio 1
	s_setprio 0
	v_mfma_f32_16x16x32_bf16 v[116:119], v[168:171], v[184:187], v[116:119]
	v_mfma_f32_16x16x32_bf16 v[112:115], v[176:179], v[184:187], v[112:115]
	v_mfma_f32_16x16x32_bf16 v[100:103], v[168:171], v[192:195], v[100:103]
	v_mfma_f32_16x16x32_bf16 v[96:99], v[176:179], v[192:195], v[96:99]
	v_mfma_f32_16x16x32_bf16 v[84:87], v[168:171], v[200:203], v[84:87]
	v_mfma_f32_16x16x32_bf16 v[80:83], v[176:179], v[200:203], v[80:83]
	v_mfma_f32_16x16x32_bf16 v[68:71], v[168:171], v[208:211], v[68:71]
	v_mfma_f32_16x16x32_bf16 v[64:67], v[176:179], v[208:211], v[64:67]
	v_mfma_f32_16x16x32_bf16 v[116:119], v[172:175], v[188:191], v[116:119]
	v_mfma_f32_16x16x32_bf16 v[112:115], v[180:183], v[188:191], v[112:115]
	v_mfma_f32_16x16x32_bf16 v[100:103], v[172:175], v[196:199], v[100:103]
	v_mfma_f32_16x16x32_bf16 v[96:99], v[180:183], v[196:199], v[96:99]
	v_mfma_f32_16x16x32_bf16 v[84:87], v[172:175], v[204:207], v[84:87]
	v_mfma_f32_16x16x32_bf16 v[80:83], v[180:183], v[204:207], v[80:83]
	v_mfma_f32_16x16x32_bf16 v[68:71], v[172:175], v[212:215], v[68:71]
	v_mfma_f32_16x16x32_bf16 v[64:67], v[180:183], v[212:215], v[64:67]
	s_setprio 1
	s_barrier
	s_add_i32 s40, s60, s44
	s_add_u32 s80, s38, 0x80
	s_addc_u32 s81, s39, 0
	s_mov_b32 m0, s40
	ds_read_b128 v[184:187], v155 offset:49152
	ds_read_b128 v[188:191], v155 offset:50176
	ds_read_b128 v[192:195], v155 offset:51200
	ds_read_b128 v[196:199], v155 offset:52224
	ds_read_b128 v[200:203], v155 offset:53248
	ds_read_b128 v[204:207], v155 offset:54272
	ds_read_b128 v[208:211], v155 offset:55296
	ds_read_b128 v[212:215], v155 offset:56320
	global_load_lds_dwordx4 v130, s[80:81]
	s_add_i32 m0, s40, 0x2000
	s_add_u32 s38, s38, 0x100080
	s_addc_u32 s39, s39, 0
	s_add_i32 s40, s61, s44
	global_load_lds_dwordx4 v134, s[80:81]
	s_mov_b32 m0, s40
	s_nop 0
	global_load_lds_dwordx4 v130, s[38:39]
	s_add_i32 m0, s40, 0x2000
	s_nop 0
	global_load_lds_dwordx4 v134, s[38:39]
	s_mov_b32 m0, s49
	s_nop 0
	global_load_lds_dwordx4 v128, s[82:83]
	s_mov_b32 m0, s50
	s_nop 0
	global_load_lds_dwordx4 v132, s[82:83]
	s_waitcnt vmcnt(8)
	s_waitcnt lgkmcnt(0)
	s_barrier
	s_setprio 0
	s_waitcnt lgkmcnt(0)
	v_mfma_f32_16x16x32_bf16 v[60:63], v[144:147], v[184:187], v[60:63]
	v_mfma_f32_16x16x32_bf16 v[56:59], v[160:163], v[184:187], v[56:59]
	v_mfma_f32_16x16x32_bf16 v[44:47], v[144:147], v[192:195], v[44:47]
	v_mfma_f32_16x16x32_bf16 v[40:43], v[160:163], v[192:195], v[40:43]
	v_mfma_f32_16x16x32_bf16 v[28:31], v[144:147], v[200:203], v[28:31]
	v_mfma_f32_16x16x32_bf16 v[24:27], v[160:163], v[200:203], v[24:27]
	v_mfma_f32_16x16x32_bf16 v[12:15], v[144:147], v[208:211], v[12:15]
	v_mfma_f32_16x16x32_bf16 v[8:11], v[160:163], v[208:211], v[8:11]
	v_mfma_f32_16x16x32_bf16 v[60:63], v[156:159], v[188:191], v[60:63]
	v_mfma_f32_16x16x32_bf16 v[56:59], v[164:167], v[188:191], v[56:59]
	v_mfma_f32_16x16x32_bf16 v[44:47], v[156:159], v[196:199], v[44:47]
	v_mfma_f32_16x16x32_bf16 v[40:43], v[164:167], v[196:199], v[40:43]
	v_mfma_f32_16x16x32_bf16 v[28:31], v[156:159], v[204:207], v[28:31]
	v_mfma_f32_16x16x32_bf16 v[24:27], v[164:167], v[204:207], v[24:27]
	v_mfma_f32_16x16x32_bf16 v[12:15], v[156:159], v[212:215], v[12:15]
	v_mfma_f32_16x16x32_bf16 v[8:11], v[164:167], v[212:215], v[8:11]
	s_setprio 1
	s_setprio 0
	v_mfma_f32_16x16x32_bf16 v[52:55], v[168:171], v[184:187], v[52:55]
	v_mfma_f32_16x16x32_bf16 v[48:51], v[176:179], v[184:187], v[48:51]
	v_mfma_f32_16x16x32_bf16 v[36:39], v[168:171], v[192:195], v[36:39]
	v_mfma_f32_16x16x32_bf16 v[32:35], v[176:179], v[192:195], v[32:35]
	v_mfma_f32_16x16x32_bf16 v[20:23], v[168:171], v[200:203], v[20:23]
	v_mfma_f32_16x16x32_bf16 v[16:19], v[176:179], v[200:203], v[16:19]
	v_mfma_f32_16x16x32_bf16 v[4:7], v[168:171], v[208:211], v[4:7]
	v_mfma_f32_16x16x32_bf16 v[0:3], v[176:179], v[208:211], v[0:3]
	v_mfma_f32_16x16x32_bf16 v[52:55], v[172:175], v[188:191], v[52:55]
	v_mfma_f32_16x16x32_bf16 v[48:51], v[180:183], v[188:191], v[48:51]
	v_mfma_f32_16x16x32_bf16 v[36:39], v[172:175], v[196:199], v[36:39]
	v_mfma_f32_16x16x32_bf16 v[32:35], v[180:183], v[196:199], v[32:35]
	v_mfma_f32_16x16x32_bf16 v[20:23], v[172:175], v[204:207], v[20:23]
	v_mfma_f32_16x16x32_bf16 v[16:19], v[180:183], v[204:207], v[16:19]
	v_mfma_f32_16x16x32_bf16 v[4:7], v[172:175], v[212:215], v[4:7]
	v_mfma_f32_16x16x32_bf16 v[0:3], v[180:183], v[212:215], v[0:3]
	s_setprio 1
	s_barrier
	s_add_i32 s59, s59, 2
	s_add_u32 s36, s36, 0x100
	s_addc_u32 s37, s37, 0
	s_add_u32 s57, s57, 0x100
	s_addc_u32 s58, s58, 0
	s_cmp_gt_u32 s59, 61
	s_cbranch_scc0 .LBB0_2102
	s_and_b64 vcc, exec, s[6:7]
	s_cbranch_vccz .LBB0_2105
	s_barrier
